# Strategy 4: GEMM K-loops with one static s_setprio 1 for waves 4-7 (later half) at loop entry, per-phase setprio pairs removed
# baseline (speedup 1.0000x reference)
; #define PG8_STAGE(bufoff, gbase, voff) do { _Pragma("unroll") for (int _i = 0; _i < 2; ++_i) \
;         __builtin_amdgcn_global_load_lds((const unsigned*)((const char*)(gbase) + (voff)[_i]), (PG8_LAS unsigned*)(lds + (bufoff) + ldsw + _i * 8192), 16, 0, 0); } while (0)
; #define PG8_LDA(dst, b, h) do { _Pragma("unroll") for (int m = 0; m < 4; ++m) _Pragma("unroll") for (int k = 0; k < 2; ++k) dst[m][k] = *(const PG8_LAS bf16x8*)(lds + PG8_SA(b, h) + aoff + m * 2048 + k * 1024); } while (0)
; #define PG8_LDB(dst, b, h) do { _Pragma("unroll") for (int n = 0; n < 2; ++n) _Pragma("unroll") for (int k = 0; k < 2; ++k) dst[n][k] = *(const PG8_LAS bf16x8*)(lds + PG8_SB(b, h) + boff + n * 2048 + k * 1024); } while (0)
; #define PG8_MMA(ai, bj, At, Bt) do { __builtin_amdgcn_s_setprio(1); _Pragma("unroll") for (int m = 0; m < 4; ++m) _Pragma("unroll") for (int n = 0; n < 2; ++n) _Pragma("unroll") for (int k = 0; k < 2; ++k) \
;         acc[ai][bj][m][n] = __builtin_amdgcn_mfma_f32_16x16x32_bf16(Bt[n][k], At[m][k], acc[ai][bj][m][n], 0, 0, 0); __builtin_amdgcn_s_setprio(0); } while (0)
; #define PG8_WAIT_V(n) asm volatile("s_waitcnt vmcnt(" #n ")" ::: "memory")
; #define PG8_WAIT_L(n) asm volatile("s_waitcnt lgkmcnt(" #n ")" ::: "memory")
; #define PG8_BAR __builtin_amdgcn_s_barrier()
; #define PG8_SCHED __builtin_amdgcn_sched_barrier(0)
; template <class Epi, class Sched, bool ALIGN_EPI = false, bool SP2 = false>
; __device__ __forceinline__ void gemm_phase(PG8_LAS unsigned char* lds, const Gemm g, const Sched& S, const Epi& E, const int tid) {
;     ...
;             PG8_LDB(B0, 0, 0); PG8_LDB(B1, 0, 1); PG8_SCHED; PG8_LDA(At, 0, 0); PG8_STAGE(PG8_SA(1, 1), a1 + hstep, voffA);
;             PG8_WAIT_V(8); PG8_WAIT_L(0); PG8_BAR; PG8_MMA(0, 0, At, B0); PG8_MMA(0, 1, At, B1); PG8_BAR; PG8_SCHED;
;     ...
; #pragma unroll
;         for (int a = 0; a < 2; ++a)
; #pragma unroll
;             for (int b = 0; b < 2; ++b)
; #pragma unroll
;                 for (int m = 0; m < 4; ++m)
; #pragma unroll
;                     for (int n = 0; n < 2; ++n) acc[a][b][m][n] = (f32x4){0.f, 0.f, 0.f, 0.f};
.LBB0_210:
	s_ashr_i32 s49, s48, 31
	s_lshl_b64 s[50:51], s[48:49], 20
	s_add_u32 s50, s2, s50
	s_addc_u32 s51, s36, s51
	s_and_b64 s[52:53], s[40:41], exec
	s_cselect_b32 s49, s51, s57
	s_cselect_b32 s72, s50, s56
	s_ashr_i32 s47, s46, 31
	s_lshl_b64 s[52:53], s[46:47], 20
	s_add_u32 s52, s38, s52
	s_addc_u32 s53, s39, s53
	s_and_b64 s[58:59], s[40:41], exec
	s_cselect_b32 s47, s53, s55
	s_cselect_b32 s73, s52, s54
	s_cselect_b32 s100, 0, 0xf00
	s_add_u32 s72, s72, s100
	s_addc_u32 s49, s49, 0
	s_add_u32 s73, s73, s100
	s_addc_u32 s47, s47, 0
	s_add_u32 s75, s54, 0x100
	s_addc_u32 s76, s55, 0
	s_add_u32 s54, s56, 0x80080
	v_mov_b32_e32 v0, 0
	s_addc_u32 s55, s57, 0
	s_mov_b32 s77, -2
	v_mov_b32_e32 v1, v0
	v_mov_b32_e32 v2, v0
	v_mov_b32_e32 v3, v0
	v_mov_b32_e32 v8, v0
	v_mov_b32_e32 v9, v0
	v_mov_b32_e32 v10, v0
	v_mov_b32_e32 v11, v0
	v_mov_b32_e32 v16, v0
	v_mov_b32_e32 v17, v0
	v_mov_b32_e32 v18, v0
	v_mov_b32_e32 v19, v0
	v_mov_b32_e32 v24, v0
	v_mov_b32_e32 v25, v0
	v_mov_b32_e32 v26, v0
	v_mov_b32_e32 v27, v0
	v_mov_b32_e32 v32, v0
	v_mov_b32_e32 v33, v0
	v_mov_b32_e32 v34, v0
	v_mov_b32_e32 v35, v0
	v_mov_b32_e32 v40, v0
	v_mov_b32_e32 v41, v0
	v_mov_b32_e32 v42, v0
	v_mov_b32_e32 v43, v0
	v_mov_b32_e32 v48, v0
	v_mov_b32_e32 v49, v0
	v_mov_b32_e32 v50, v0
	v_mov_b32_e32 v51, v0
	v_mov_b32_e32 v56, v0
	v_mov_b32_e32 v57, v0
	v_mov_b32_e32 v58, v0
	v_mov_b32_e32 v59, v0
	v_mov_b32_e32 v4, v0
	v_mov_b32_e32 v5, v0
	v_mov_b32_e32 v6, v0
	v_mov_b32_e32 v7, v0
	v_mov_b32_e32 v12, v0
	v_mov_b32_e32 v13, v0
	v_mov_b32_e32 v14, v0
	v_mov_b32_e32 v15, v0
	v_mov_b32_e32 v20, v0
	v_mov_b32_e32 v21, v0
	v_mov_b32_e32 v22, v0
	v_mov_b32_e32 v23, v0
	v_mov_b32_e32 v28, v0
	v_mov_b32_e32 v29, v0
	v_mov_b32_e32 v30, v0
	v_mov_b32_e32 v31, v0
	v_mov_b32_e32 v36, v0
	v_mov_b32_e32 v37, v0
	v_mov_b32_e32 v38, v0
	v_mov_b32_e32 v39, v0
	v_mov_b32_e32 v44, v0
	v_mov_b32_e32 v45, v0
	v_mov_b32_e32 v46, v0
	v_mov_b32_e32 v47, v0
	v_mov_b32_e32 v52, v0
	v_mov_b32_e32 v53, v0
	v_mov_b32_e32 v54, v0
	v_mov_b32_e32 v55, v0
	v_mov_b32_e32 v60, v0
	v_mov_b32_e32 v61, v0
	v_mov_b32_e32 v62, v0
	v_mov_b32_e32 v63, v0
	v_mov_b32_e32 v64, v0
	v_mov_b32_e32 v65, v0
	v_mov_b32_e32 v66, v0
	v_mov_b32_e32 v67, v0
	v_mov_b32_e32 v72, v0
	v_mov_b32_e32 v73, v0
	v_mov_b32_e32 v74, v0
	v_mov_b32_e32 v75, v0
	v_mov_b32_e32 v80, v0
	v_mov_b32_e32 v81, v0
	v_mov_b32_e32 v82, v0
	v_mov_b32_e32 v83, v0
	v_mov_b32_e32 v88, v0
	v_mov_b32_e32 v89, v0
	v_mov_b32_e32 v90, v0
	v_mov_b32_e32 v91, v0
	v_mov_b32_e32 v102, v0
	v_mov_b32_e32 v103, v0
	v_mov_b32_e32 v104, v0
	v_mov_b32_e32 v105, v0
	v_mov_b32_e32 v110, v0
	v_mov_b32_e32 v111, v0
	v_mov_b32_e32 v112, v0
	v_mov_b32_e32 v113, v0
	v_mov_b32_e32 v118, v0
	v_mov_b32_e32 v119, v0
	v_mov_b32_e32 v120, v0
	v_mov_b32_e32 v121, v0
	v_mov_b32_e32 v122, v0
	v_mov_b32_e32 v123, v0
	v_mov_b32_e32 v124, v0
	v_mov_b32_e32 v125, v0
	v_mov_b32_e32 v68, v0
	v_mov_b32_e32 v69, v0
	v_mov_b32_e32 v70, v0
	v_mov_b32_e32 v71, v0
	v_mov_b32_e32 v76, v0
	v_mov_b32_e32 v77, v0
	v_mov_b32_e32 v78, v0
	v_mov_b32_e32 v79, v0
	v_mov_b32_e32 v84, v0
	v_mov_b32_e32 v85, v0
	v_mov_b32_e32 v86, v0
	v_mov_b32_e32 v87, v0
	v_mov_b32_e32 v92, v0
	v_mov_b32_e32 v93, v0
	v_mov_b32_e32 v94, v0
	v_mov_b32_e32 v95, v0
	v_mov_b32_e32 v106, v0
	v_mov_b32_e32 v107, v0
	v_mov_b32_e32 v108, v0
	v_mov_b32_e32 v109, v0
	v_mov_b32_e32 v114, v0
	v_mov_b32_e32 v115, v0
	v_mov_b32_e32 v116, v0
	v_mov_b32_e32 v117, v0
	v_mov_b32_e32 v126, v0
	v_mov_b32_e32 v127, v0
	v_mov_b32_e32 v128, v0
	v_mov_b32_e32 v129, v0
	v_mov_b32_e32 v130, v0
	v_mov_b32_e32 v131, v0
	v_mov_b32_e32 v132, v0
	v_mov_b32_e32 v133, v0
	s_cmp_gt_u32 s81, 0xff
	s_cbranch_scc0 .Lsp_211
	s_setprio 1
.Lsp_211:
.LBB0_211:
	s_add_u32 s56, s54, 0xfff80080
	s_addc_u32 s57, s55, -1
	s_add_i32 s78, 0, 0x10000
	s_cmp_eq_u32 s77, 28
	s_cselect_b32 s59, s49, s57
	s_cselect_b32 s58, s72, s56
	s_cselect_b32 s57, s47, s76
	s_cselect_b32 s56, s73, s75
	s_add_i32 s80, 0, 0x14000
	v_add_u32_e32 v154, s78, v160
	v_add_u32_e32 v158, s80, v160
	ds_read_b128 v[142:145], v154
	ds_read_b128 v[146:149], v154 offset:1024
	ds_read_b128 v[150:153], v154 offset:2048
	ds_read_b128 v[154:157], v154 offset:3072
	ds_read_b128 v[164:167], v158
	ds_read_b128 v[168:171], v158 offset:1024
	ds_read_b128 v[172:175], v158 offset:2048
	ds_read_b128 v[176:179], v158 offset:3072
	v_lshl_add_u64 v[158:159], s[54:55], 0, v[140:141]
	s_add_i32 m0, s61, 0xc000
	ds_read_b128 v[186:189], v162
	ds_read_b128 v[190:193], v162 offset:1024
	ds_read_b128 v[194:197], v162 offset:2048
	ds_read_b128 v[198:201], v162 offset:3072
	ds_read_b128 v[202:205], v162 offset:4096
	ds_read_b128 v[206:209], v162 offset:5120
	ds_read_b128 v[210:213], v162 offset:6144
	ds_read_b128 v[214:217], v162 offset:7168
	global_load_lds_dwordx4 v[158:159], off
	v_lshl_add_u64 v[158:159], s[54:55], 0, v[138:139]
	s_add_i32 m0, s61, 0xe000
	s_nop 0
	global_load_lds_dwordx4 v[158:159], off
	s_waitcnt vmcnt(8)
	s_waitcnt lgkmcnt(0)
	s_barrier
; #define PG8_STAGE(bufoff, gbase, voff) do { _Pragma("unroll") for (int _i = 0; _i < 2; ++_i) \
;         __builtin_amdgcn_global_load_lds((const unsigned*)((const char*)(gbase) + (voff)[_i]), (PG8_LAS unsigned*)(lds + (bufoff) + ldsw + _i * 8192), 16, 0, 0); } while (0)
; #define PG8_LDA(dst, b, h) do { _Pragma("unroll") for (int m = 0; m < 4; ++m) _Pragma("unroll") for (int k = 0; k < 2; ++k) dst[m][k] = *(const PG8_LAS bf16x8*)(lds + PG8_SA(b, h) + aoff + m * 2048 + k * 1024); } while (0)
; #define PG8_MMA(ai, bj, At, Bt) do { __builtin_amdgcn_s_setprio(1); _Pragma("unroll") for (int m = 0; m < 4; ++m) _Pragma("unroll") for (int n = 0; n < 2; ++n) _Pragma("unroll") for (int k = 0; k < 2; ++k) \
;         acc[ai][bj][m][n] = __builtin_amdgcn_mfma_f32_16x16x32_bf16(Bt[n][k], At[m][k], acc[ai][bj][m][n], 0, 0, 0); __builtin_amdgcn_s_setprio(0); } while (0)
; #define PG8_WAIT_V(n) asm volatile("s_waitcnt vmcnt(" #n ")" ::: "memory")
; #define PG8_WAIT_L(n) asm volatile("s_waitcnt lgkmcnt(" #n ")" ::: "memory")
; #define PG8_BAR __builtin_amdgcn_s_barrier()
; #define PG8_SCHED __builtin_amdgcn_sched_barrier(0)
; template <class Epi, class Sched, bool ALIGN_EPI = false, bool SP2 = false>
; __device__ __forceinline__ void gemm_phase(PG8_LAS unsigned char* lds, const Gemm g, const Sched& S, const Epi& E, const int tid) {
;     ...
;             PG8_WAIT_V(8); PG8_WAIT_L(0); PG8_BAR; PG8_MMA(0, 0, At, B0); PG8_MMA(0, 1, At, B1); PG8_BAR; PG8_SCHED;
;             PG8_LDA(At, 0, 1); PG8_STAGE(PG8_SB(0, 0), b2, voffB); PG8_STAGE(PG8_SB(0, 1), b2 + hstep, voffB); PG8_STAGE(PG8_SA(0, 0), a2, voffA);
;             PG8_WAIT_V(8); PG8_WAIT_L(0); PG8_BAR; PG8_MMA(1, 0, At, B0); PG8_MMA(1, 1, At, B1); PG8_BAR; PG8_SCHED;
	v_mfma_f32_16x16x32_bf16 v[130:133], v[142:145], v[186:189], v[130:133]
	v_mfma_f32_16x16x32_bf16 v[126:129], v[150:153], v[186:189], v[126:129]
	v_mfma_f32_16x16x32_bf16 v[114:117], v[142:145], v[194:197], v[114:117]
	v_mfma_f32_16x16x32_bf16 v[106:109], v[150:153], v[194:197], v[106:109]
	v_mfma_f32_16x16x32_bf16 v[92:95], v[142:145], v[202:205], v[92:95]
	v_mfma_f32_16x16x32_bf16 v[84:87], v[150:153], v[202:205], v[84:87]
	v_mfma_f32_16x16x32_bf16 v[76:79], v[142:145], v[210:213], v[76:79]
	v_mfma_f32_16x16x32_bf16 v[68:71], v[150:153], v[210:213], v[68:71]
	v_mfma_f32_16x16x32_bf16 v[130:133], v[146:149], v[190:193], v[130:133]
	v_mfma_f32_16x16x32_bf16 v[126:129], v[154:157], v[190:193], v[126:129]
	v_mfma_f32_16x16x32_bf16 v[114:117], v[146:149], v[198:201], v[114:117]
	v_mfma_f32_16x16x32_bf16 v[106:109], v[154:157], v[198:201], v[106:109]
	v_mfma_f32_16x16x32_bf16 v[92:95], v[146:149], v[206:209], v[92:95]
	v_mfma_f32_16x16x32_bf16 v[84:87], v[154:157], v[206:209], v[84:87]
	v_mfma_f32_16x16x32_bf16 v[76:79], v[146:149], v[214:217], v[76:79]
	v_mfma_f32_16x16x32_bf16 v[68:71], v[154:157], v[214:217], v[68:71]
	v_mfma_f32_16x16x32_bf16 v[122:125], v[164:167], v[186:189], v[122:125]
	v_mfma_f32_16x16x32_bf16 v[118:121], v[172:175], v[186:189], v[118:121]
	v_mfma_f32_16x16x32_bf16 v[110:113], v[164:167], v[194:197], v[110:113]
	v_mfma_f32_16x16x32_bf16 v[102:105], v[172:175], v[194:197], v[102:105]
	v_mfma_f32_16x16x32_bf16 v[88:91], v[164:167], v[202:205], v[88:91]
	v_mfma_f32_16x16x32_bf16 v[80:83], v[172:175], v[202:205], v[80:83]
	v_mfma_f32_16x16x32_bf16 v[72:75], v[164:167], v[210:213], v[72:75]
	v_mfma_f32_16x16x32_bf16 v[64:67], v[172:175], v[210:213], v[64:67]
	v_mfma_f32_16x16x32_bf16 v[122:125], v[168:171], v[190:193], v[122:125]
	v_mfma_f32_16x16x32_bf16 v[118:121], v[176:179], v[190:193], v[118:121]
	v_mfma_f32_16x16x32_bf16 v[110:113], v[168:171], v[198:201], v[110:113]
	v_mfma_f32_16x16x32_bf16 v[102:105], v[176:179], v[198:201], v[102:105]
	v_mfma_f32_16x16x32_bf16 v[88:91], v[168:171], v[206:209], v[88:91]
	v_mfma_f32_16x16x32_bf16 v[80:83], v[176:179], v[206:209], v[80:83]
	v_mfma_f32_16x16x32_bf16 v[72:75], v[168:171], v[214:217], v[72:75]
	v_mfma_f32_16x16x32_bf16 v[64:67], v[176:179], v[214:217], v[64:67]
	s_barrier
	s_add_i32 s78, s78, s60
	v_lshl_add_u64 v[158:159], s[56:57], 0, v[96:97]
	s_mov_b32 m0, s78
	ds_read_b128 v[186:189], v162 offset:16384
	ds_read_b128 v[190:193], v162 offset:17408
	ds_read_b128 v[194:197], v162 offset:18432
	ds_read_b128 v[198:201], v162 offset:19456
	ds_read_b128 v[202:205], v162 offset:20480
	ds_read_b128 v[206:209], v162 offset:21504
	ds_read_b128 v[210:213], v162 offset:22528
	ds_read_b128 v[214:217], v162 offset:23552
	global_load_lds_dwordx4 v[158:159], off
	s_add_i32 m0, s78, 0x2000
	s_add_u32 s78, s56, 0x80000
	v_lshl_add_u64 v[180:181], s[56:57], 0, v[98:99]
	s_addc_u32 s79, s57, 0
	s_add_i32 s80, s80, s60
	global_load_lds_dwordx4 v[180:181], off
	v_lshl_add_u64 v[218:219], s[78:79], 0, v[96:97]
	s_mov_b32 m0, s80
	v_lshl_add_u64 v[220:221], s[58:59], 0, v[134:135]
	global_load_lds_dwordx4 v[218:219], off
	v_lshl_add_u64 v[218:219], s[78:79], 0, v[98:99]
	s_add_i32 m0, s80, 0x2000
	s_nop 0
	global_load_lds_dwordx4 v[218:219], off
	v_lshl_add_u64 v[218:219], s[58:59], 0, v[136:137]
	s_mov_b32 m0, s61
	s_nop 0
	global_load_lds_dwordx4 v[218:219], off
	s_mov_b32 m0, s64
	s_nop 0
	global_load_lds_dwordx4 v[220:221], off
	s_waitcnt vmcnt(8)
	s_waitcnt lgkmcnt(0)
	s_barrier
	v_mfma_f32_16x16x32_bf16 v[60:63], v[142:145], v[186:189], v[60:63]
	v_mfma_f32_16x16x32_bf16 v[52:55], v[150:153], v[186:189], v[52:55]
	v_mfma_f32_16x16x32_bf16 v[44:47], v[142:145], v[194:197], v[44:47]
	v_mfma_f32_16x16x32_bf16 v[36:39], v[150:153], v[194:197], v[36:39]
	v_mfma_f32_16x16x32_bf16 v[28:31], v[142:145], v[202:205], v[28:31]
	v_mfma_f32_16x16x32_bf16 v[20:23], v[150:153], v[202:205], v[20:23]
	v_mfma_f32_16x16x32_bf16 v[12:15], v[142:145], v[210:213], v[12:15]
	v_mfma_f32_16x16x32_bf16 v[4:7], v[150:153], v[210:213], v[4:7]
	v_mfma_f32_16x16x32_bf16 v[60:63], v[146:149], v[190:193], v[60:63]
	v_mfma_f32_16x16x32_bf16 v[52:55], v[154:157], v[190:193], v[52:55]
	v_mfma_f32_16x16x32_bf16 v[44:47], v[146:149], v[198:201], v[44:47]
	v_mfma_f32_16x16x32_bf16 v[36:39], v[154:157], v[198:201], v[36:39]
	v_mfma_f32_16x16x32_bf16 v[28:31], v[146:149], v[206:209], v[28:31]
	v_mfma_f32_16x16x32_bf16 v[20:23], v[154:157], v[206:209], v[20:23]
	v_mfma_f32_16x16x32_bf16 v[12:15], v[146:149], v[214:217], v[12:15]
	v_mfma_f32_16x16x32_bf16 v[4:7], v[154:157], v[214:217], v[4:7]
	v_mfma_f32_16x16x32_bf16 v[56:59], v[164:167], v[186:189], v[56:59]
	v_mfma_f32_16x16x32_bf16 v[48:51], v[172:175], v[186:189], v[48:51]
	v_mfma_f32_16x16x32_bf16 v[40:43], v[164:167], v[194:197], v[40:43]
	v_mfma_f32_16x16x32_bf16 v[32:35], v[172:175], v[194:197], v[32:35]
	v_mfma_f32_16x16x32_bf16 v[24:27], v[164:167], v[202:205], v[24:27]
	v_mfma_f32_16x16x32_bf16 v[16:19], v[172:175], v[202:205], v[16:19]
	v_mfma_f32_16x16x32_bf16 v[8:11], v[164:167], v[210:213], v[8:11]
	v_mfma_f32_16x16x32_bf16 v[0:3], v[172:175], v[210:213], v[0:3]
	v_mfma_f32_16x16x32_bf16 v[56:59], v[168:171], v[190:193], v[56:59]
	v_mfma_f32_16x16x32_bf16 v[48:51], v[176:179], v[190:193], v[48:51]
	v_mfma_f32_16x16x32_bf16 v[40:43], v[168:171], v[198:201], v[40:43]
	v_mfma_f32_16x16x32_bf16 v[32:35], v[176:179], v[198:201], v[32:35]
	v_mfma_f32_16x16x32_bf16 v[24:27], v[168:171], v[206:209], v[24:27]
	v_mfma_f32_16x16x32_bf16 v[16:19], v[176:179], v[206:209], v[16:19]
	v_mfma_f32_16x16x32_bf16 v[8:11], v[168:171], v[214:217], v[8:11]
	v_mfma_f32_16x16x32_bf16 v[0:3], v[176:179], v[214:217], v[0:3]
	s_barrier
; #define PG8_STAGE(bufoff, gbase, voff) do { _Pragma("unroll") for (int _i = 0; _i < 2; ++_i) \
;         __builtin_amdgcn_global_load_lds((const unsigned*)((const char*)(gbase) + (voff)[_i]), (PG8_LAS unsigned*)(lds + (bufoff) + ldsw + _i * 8192), 16, 0, 0); } while (0)
; #define PG8_LDA(dst, b, h) do { _Pragma("unroll") for (int m = 0; m < 4; ++m) _Pragma("unroll") for (int k = 0; k < 2; ++k) dst[m][k] = *(const PG8_LAS bf16x8*)(lds + PG8_SA(b, h) + aoff + m * 2048 + k * 1024); } while (0)
; #define PG8_LDB(dst, b, h) do { _Pragma("unroll") for (int n = 0; n < 2; ++n) _Pragma("unroll") for (int k = 0; k < 2; ++k) dst[n][k] = *(const PG8_LAS bf16x8*)(lds + PG8_SB(b, h) + boff + n * 2048 + k * 1024); } while (0)
; #define PG8_MMA(ai, bj, At, Bt) do { __builtin_amdgcn_s_setprio(1); _Pragma("unroll") for (int m = 0; m < 4; ++m) _Pragma("unroll") for (int n = 0; n < 2; ++n) _Pragma("unroll") for (int k = 0; k < 2; ++k) \
;         acc[ai][bj][m][n] = __builtin_amdgcn_mfma_f32_16x16x32_bf16(Bt[n][k], At[m][k], acc[ai][bj][m][n], 0, 0, 0); __builtin_amdgcn_s_setprio(0); } while (0)
; #define PG8_WAIT_V(n) asm volatile("s_waitcnt vmcnt(" #n ")" ::: "memory")
; #define PG8_WAIT_L(n) asm volatile("s_waitcnt lgkmcnt(" #n ")" ::: "memory")
; #define PG8_BAR __builtin_amdgcn_s_barrier()
; #define PG8_SCHED __builtin_amdgcn_sched_barrier(0)
; template <class Epi, class Sched, bool ALIGN_EPI = false, bool SP2 = false>
; __device__ __forceinline__ void gemm_phase(PG8_LAS unsigned char* lds, const Gemm g, const Sched& S, const Epi& E, const int tid) {
;     ...
;             PG8_LDB(B0, 1, 0); PG8_LDB(B1, 1, 1); PG8_SCHED; PG8_LDA(At, 1, 0); PG8_STAGE(PG8_SA(0, 1), a2 + hstep, voffA);
;             PG8_WAIT_V(8); PG8_WAIT_L(0); PG8_BAR; PG8_MMA(0, 0, At, B0); PG8_MMA(0, 1, At, B1); PG8_BAR; PG8_SCHED;
	s_add_i32 s78, 0, 0x18000
	s_add_i32 s79, 0, 0x1c000
	v_add_u32_e32 v154, s78, v160
	v_add_u32_e32 v163, s79, v160
	ds_read_b128 v[142:145], v154
	ds_read_b128 v[146:149], v154 offset:1024
	ds_read_b128 v[150:153], v154 offset:2048
	ds_read_b128 v[154:157], v154 offset:3072
	ds_read_b128 v[164:167], v163
	ds_read_b128 v[168:171], v163 offset:1024
	ds_read_b128 v[172:175], v163 offset:2048
	ds_read_b128 v[176:179], v163 offset:3072
	s_add_u32 s58, s58, 0x80000
	s_addc_u32 s59, s59, 0
	s_mov_b32 m0, s65
	v_lshl_add_u64 v[222:223], s[58:59], 0, v[136:137]
	ds_read_b128 v[186:189], v162 offset:32768
	ds_read_b128 v[190:193], v162 offset:33792
	ds_read_b128 v[194:197], v162 offset:34816
	ds_read_b128 v[198:201], v162 offset:35840
	ds_read_b128 v[202:205], v162 offset:36864
	ds_read_b128 v[206:209], v162 offset:37888
	ds_read_b128 v[210:213], v162 offset:38912
	ds_read_b128 v[214:217], v162 offset:39936
	global_load_lds_dwordx4 v[222:223], off
	v_lshl_add_u64 v[222:223], s[58:59], 0, v[134:135]
	s_mov_b32 m0, s66
	s_nop 0
	global_load_lds_dwordx4 v[222:223], off
	s_waitcnt vmcnt(8)
	s_waitcnt lgkmcnt(0)
	s_barrier
	v_mfma_f32_16x16x32_bf16 v[130:133], v[142:145], v[186:189], v[130:133]
	v_mfma_f32_16x16x32_bf16 v[126:129], v[150:153], v[186:189], v[126:129]
	v_mfma_f32_16x16x32_bf16 v[114:117], v[142:145], v[194:197], v[114:117]
	v_mfma_f32_16x16x32_bf16 v[106:109], v[150:153], v[194:197], v[106:109]
	v_mfma_f32_16x16x32_bf16 v[92:95], v[142:145], v[202:205], v[92:95]
	v_mfma_f32_16x16x32_bf16 v[84:87], v[150:153], v[202:205], v[84:87]
	v_mfma_f32_16x16x32_bf16 v[76:79], v[142:145], v[210:213], v[76:79]
	v_mfma_f32_16x16x32_bf16 v[68:71], v[150:153], v[210:213], v[68:71]
	v_mfma_f32_16x16x32_bf16 v[130:133], v[146:149], v[190:193], v[130:133]
	v_mfma_f32_16x16x32_bf16 v[126:129], v[154:157], v[190:193], v[126:129]
	v_mfma_f32_16x16x32_bf16 v[114:117], v[146:149], v[198:201], v[114:117]
	v_mfma_f32_16x16x32_bf16 v[106:109], v[154:157], v[198:201], v[106:109]
	v_mfma_f32_16x16x32_bf16 v[92:95], v[146:149], v[206:209], v[92:95]
	v_mfma_f32_16x16x32_bf16 v[84:87], v[154:157], v[206:209], v[84:87]
	v_mfma_f32_16x16x32_bf16 v[76:79], v[146:149], v[214:217], v[76:79]
	v_mfma_f32_16x16x32_bf16 v[68:71], v[154:157], v[214:217], v[68:71]
	v_mfma_f32_16x16x32_bf16 v[122:125], v[164:167], v[186:189], v[122:125]
	v_mfma_f32_16x16x32_bf16 v[118:121], v[172:175], v[186:189], v[118:121]
	v_mfma_f32_16x16x32_bf16 v[110:113], v[164:167], v[194:197], v[110:113]
	v_mfma_f32_16x16x32_bf16 v[102:105], v[172:175], v[194:197], v[102:105]
	v_mfma_f32_16x16x32_bf16 v[88:91], v[164:167], v[202:205], v[88:91]
	v_mfma_f32_16x16x32_bf16 v[80:83], v[172:175], v[202:205], v[80:83]
	v_mfma_f32_16x16x32_bf16 v[72:75], v[164:167], v[210:213], v[72:75]
	v_mfma_f32_16x16x32_bf16 v[64:67], v[172:175], v[210:213], v[64:67]
	v_mfma_f32_16x16x32_bf16 v[122:125], v[168:171], v[190:193], v[122:125]
	v_mfma_f32_16x16x32_bf16 v[118:121], v[176:179], v[190:193], v[118:121]
	v_mfma_f32_16x16x32_bf16 v[110:113], v[168:171], v[198:201], v[110:113]
	v_mfma_f32_16x16x32_bf16 v[102:105], v[176:179], v[198:201], v[102:105]
	v_mfma_f32_16x16x32_bf16 v[88:91], v[168:171], v[206:209], v[88:91]
	v_mfma_f32_16x16x32_bf16 v[80:83], v[176:179], v[206:209], v[80:83]
	v_mfma_f32_16x16x32_bf16 v[72:75], v[168:171], v[214:217], v[72:75]
	v_mfma_f32_16x16x32_bf16 v[64:67], v[176:179], v[214:217], v[64:67]
	s_barrier
; #define PG8_STAGE(bufoff, gbase, voff) do { _Pragma("unroll") for (int _i = 0; _i < 2; ++_i) \
;         __builtin_amdgcn_global_load_lds((const unsigned*)((const char*)(gbase) + (voff)[_i]), (PG8_LAS unsigned*)(lds + (bufoff) + ldsw + _i * 8192), 16, 0, 0); } while (0)
; #define PG8_LDA(dst, b, h) do { _Pragma("unroll") for (int m = 0; m < 4; ++m) _Pragma("unroll") for (int k = 0; k < 2; ++k) dst[m][k] = *(const PG8_LAS bf16x8*)(lds + PG8_SA(b, h) + aoff + m * 2048 + k * 1024); } while (0)
; #define PG8_MMA(ai, bj, At, Bt) do { __builtin_amdgcn_s_setprio(1); _Pragma("unroll") for (int m = 0; m < 4; ++m) _Pragma("unroll") for (int n = 0; n < 2; ++n) _Pragma("unroll") for (int k = 0; k < 2; ++k) \
;         acc[ai][bj][m][n] = __builtin_amdgcn_mfma_f32_16x16x32_bf16(Bt[n][k], At[m][k], acc[ai][bj][m][n], 0, 0, 0); __builtin_amdgcn_s_setprio(0); } while (0)
; #define PG8_WAIT_V(n) asm volatile("s_waitcnt vmcnt(" #n ")" ::: "memory")
; #define PG8_WAIT_L(n) asm volatile("s_waitcnt lgkmcnt(" #n ")" ::: "memory")
; #define PG8_BAR __builtin_amdgcn_s_barrier()
; #define PG8_SCHED __builtin_amdgcn_sched_barrier(0)
; template <class Epi, class Sched, bool ALIGN_EPI = false, bool SP2 = false>
; __device__ __forceinline__ void gemm_phase(PG8_LAS unsigned char* lds, const Gemm g, const Sched& S, const Epi& E, const int tid) {
;     ...
;             PG8_LDA(At, 1, 1); PG8_STAGE(PG8_SB(1, 0), b3, voffB); PG8_STAGE(PG8_SB(1, 1), b3 + hstep, voffB); PG8_STAGE(PG8_SA(1, 0), a3, voffA);
;             PG8_WAIT_V(8); PG8_WAIT_L(0); PG8_BAR; PG8_MMA(1, 0, At, B0); PG8_MMA(1, 1, At, B1); PG8_BAR; PG8_SCHED;
;     ...
;         if constexpr (ALIGN_EPI) { if (wr == 0) PG8_BAR; }
	s_add_i32 s58, s78, s60
	v_lshl_add_u64 v[158:159], v[158:159], 0, s[28:29]
	s_mov_b32 m0, s58
	ds_read_b128 v[186:189], v162 offset:49152
	ds_read_b128 v[190:193], v162 offset:50176
	ds_read_b128 v[194:197], v162 offset:51200
	ds_read_b128 v[198:201], v162 offset:52224
	ds_read_b128 v[202:205], v162 offset:53248
	ds_read_b128 v[206:209], v162 offset:54272
	ds_read_b128 v[210:213], v162 offset:55296
	ds_read_b128 v[214:217], v162 offset:56320
	global_load_lds_dwordx4 v[158:159], off
	s_add_i32 m0, s58, 0x2000
	s_add_u32 s56, s56, 0x80080
	v_lshl_add_u64 v[158:159], v[180:181], 0, s[28:29]
	s_addc_u32 s57, s57, 0
	s_add_i32 s58, s79, s60
	global_load_lds_dwordx4 v[158:159], off
	v_lshl_add_u64 v[158:159], s[56:57], 0, v[96:97]
	s_mov_b32 m0, s58
	s_nop 0
	global_load_lds_dwordx4 v[158:159], off
	v_lshl_add_u64 v[158:159], s[56:57], 0, v[98:99]
	s_add_i32 m0, s58, 0x2000
	s_nop 0
	global_load_lds_dwordx4 v[158:159], off
	v_lshl_add_u64 v[158:159], v[218:219], 0, s[28:29]
	s_mov_b32 m0, s67
	s_nop 0
	global_load_lds_dwordx4 v[158:159], off
	v_lshl_add_u64 v[158:159], v[220:221], 0, s[28:29]
	s_mov_b32 m0, s68
	s_nop 0
	global_load_lds_dwordx4 v[158:159], off
	s_waitcnt vmcnt(8)
	s_waitcnt lgkmcnt(0)
	s_barrier
	v_mfma_f32_16x16x32_bf16 v[60:63], v[142:145], v[186:189], v[60:63]
	v_mfma_f32_16x16x32_bf16 v[52:55], v[150:153], v[186:189], v[52:55]
	v_mfma_f32_16x16x32_bf16 v[44:47], v[142:145], v[194:197], v[44:47]
	v_mfma_f32_16x16x32_bf16 v[36:39], v[150:153], v[194:197], v[36:39]
	v_mfma_f32_16x16x32_bf16 v[28:31], v[142:145], v[202:205], v[28:31]
	v_mfma_f32_16x16x32_bf16 v[20:23], v[150:153], v[202:205], v[20:23]
	v_mfma_f32_16x16x32_bf16 v[12:15], v[142:145], v[210:213], v[12:15]
	v_mfma_f32_16x16x32_bf16 v[4:7], v[150:153], v[210:213], v[4:7]
	v_mfma_f32_16x16x32_bf16 v[60:63], v[146:149], v[190:193], v[60:63]
	v_mfma_f32_16x16x32_bf16 v[52:55], v[154:157], v[190:193], v[52:55]
	v_mfma_f32_16x16x32_bf16 v[44:47], v[146:149], v[198:201], v[44:47]
	v_mfma_f32_16x16x32_bf16 v[36:39], v[154:157], v[198:201], v[36:39]
	v_mfma_f32_16x16x32_bf16 v[28:31], v[146:149], v[206:209], v[28:31]
	v_mfma_f32_16x16x32_bf16 v[20:23], v[154:157], v[206:209], v[20:23]
	v_mfma_f32_16x16x32_bf16 v[12:15], v[146:149], v[214:217], v[12:15]
	v_mfma_f32_16x16x32_bf16 v[4:7], v[154:157], v[214:217], v[4:7]
	v_mfma_f32_16x16x32_bf16 v[56:59], v[164:167], v[186:189], v[56:59]
	v_mfma_f32_16x16x32_bf16 v[48:51], v[172:175], v[186:189], v[48:51]
	v_mfma_f32_16x16x32_bf16 v[40:43], v[164:167], v[194:197], v[40:43]
	v_mfma_f32_16x16x32_bf16 v[32:35], v[172:175], v[194:197], v[32:35]
	v_mfma_f32_16x16x32_bf16 v[24:27], v[164:167], v[202:205], v[24:27]
	v_mfma_f32_16x16x32_bf16 v[16:19], v[172:175], v[202:205], v[16:19]
	v_mfma_f32_16x16x32_bf16 v[8:11], v[164:167], v[210:213], v[8:11]
	v_mfma_f32_16x16x32_bf16 v[0:3], v[172:175], v[210:213], v[0:3]
	v_mfma_f32_16x16x32_bf16 v[56:59], v[168:171], v[190:193], v[56:59]
	v_mfma_f32_16x16x32_bf16 v[48:51], v[176:179], v[190:193], v[48:51]
	v_mfma_f32_16x16x32_bf16 v[40:43], v[168:171], v[198:201], v[40:43]
	v_mfma_f32_16x16x32_bf16 v[32:35], v[176:179], v[198:201], v[32:35]
	v_mfma_f32_16x16x32_bf16 v[24:27], v[168:171], v[206:209], v[24:27]
	v_mfma_f32_16x16x32_bf16 v[16:19], v[176:179], v[206:209], v[16:19]
	v_mfma_f32_16x16x32_bf16 v[8:11], v[168:171], v[214:217], v[8:11]
	v_mfma_f32_16x16x32_bf16 v[0:3], v[176:179], v[214:217], v[0:3]
	s_barrier
	s_add_i32 s77, s77, 2
	s_add_u32 s75, s75, 0x100
	s_addc_u32 s76, s76, 0
	s_add_u32 s54, s54, 0x100
	s_addc_u32 s55, s55, 0
	s_cmp_gt_u32 s77, 29
	s_cbranch_scc0 .LBB0_211
	s_setprio 0
	s_and_b64 vcc, exec, s[44:45]
	s_cbranch_vccz .LBB0_214
	s_barrier

; #define PG8_STAGE(bufoff, gbase, voff) do { _Pragma("unroll") for (int _i = 0; _i < 2; ++_i) \
;         __builtin_amdgcn_global_load_lds((const unsigned*)((const char*)(gbase) + (voff)[_i]), (PG8_LAS unsigned*)(lds + (bufoff) + ldsw + _i * 8192), 16, 0, 0); } while (0)
; #define PG8_LDA(dst, b, h) do { _Pragma("unroll") for (int m = 0; m < 4; ++m) _Pragma("unroll") for (int k = 0; k < 2; ++k) dst[m][k] = *(const PG8_LAS bf16x8*)(lds + PG8_SA(b, h) + aoff + m * 2048 + k * 1024); } while (0)
; #define PG8_LDB(dst, b, h) do { _Pragma("unroll") for (int n = 0; n < 2; ++n) _Pragma("unroll") for (int k = 0; k < 2; ++k) dst[n][k] = *(const PG8_LAS bf16x8*)(lds + PG8_SB(b, h) + boff + n * 2048 + k * 1024); } while (0)
; #define PG8_MMA(ai, bj, At, Bt) do { __builtin_amdgcn_s_setprio(1); _Pragma("unroll") for (int m = 0; m < 4; ++m) _Pragma("unroll") for (int n = 0; n < 2; ++n) _Pragma("unroll") for (int k = 0; k < 2; ++k) \
;         acc[ai][bj][m][n] = __builtin_amdgcn_mfma_f32_16x16x32_bf16(Bt[n][k], At[m][k], acc[ai][bj][m][n], 0, 0, 0); __builtin_amdgcn_s_setprio(0); } while (0)
; #define PG8_WAIT_V(n) asm volatile("s_waitcnt vmcnt(" #n ")" ::: "memory")
; #define PG8_WAIT_L(n) asm volatile("s_waitcnt lgkmcnt(" #n ")" ::: "memory")
; #define PG8_BAR __builtin_amdgcn_s_barrier()
; #define PG8_SCHED __builtin_amdgcn_sched_barrier(0)
; template <class Epi, class Sched, bool ALIGN_EPI = false, bool SP2 = false>
; __device__ __forceinline__ void gemm_phase(PG8_LAS unsigned char* lds, const Gemm g, const Sched& S, const Epi& E, const int tid) {
;     ...
;             PG8_LDB(B0, 0, 0); PG8_LDB(B1, 0, 1); PG8_SCHED; PG8_LDA(At, 0, 0); PG8_STAGE(PG8_SA(1, 1), a1 + hstep, voffA);
;             PG8_WAIT_V(8); PG8_WAIT_L(0); PG8_BAR; PG8_MMA(0, 0, At, B0); PG8_MMA(0, 1, At, B1); PG8_BAR; PG8_SCHED;
;     ...
; #pragma unroll
;         for (int a = 0; a < 2; ++a)
; #pragma unroll
;             for (int b = 0; b < 2; ++b)
; #pragma unroll
;                 for (int m = 0; m < 4; ++m)
; #pragma unroll
;                     for (int n = 0; n < 2; ++n) acc[a][b][m][n] = (f32x4){0.f, 0.f, 0.f, 0.f};
.LBB0_402:
	s_add_u32 s72, s52, 0x100
	v_mov_b32_e32 v0, 0
	s_addc_u32 s73, s53, 0
	s_mov_b32 s75, -2
	s_waitcnt lgkmcnt(0)
	v_mov_b32_e32 v1, v0
	v_mov_b32_e32 v2, v0
	v_mov_b32_e32 v3, v0
	v_mov_b32_e32 v4, v0
	v_mov_b32_e32 v5, v0
	v_mov_b32_e32 v6, v0
	v_mov_b32_e32 v7, v0
	v_mov_b32_e32 v16, v0
	v_mov_b32_e32 v17, v0
	v_mov_b32_e32 v18, v0
	v_mov_b32_e32 v19, v0
	v_mov_b32_e32 v20, v0
	v_mov_b32_e32 v21, v0
	v_mov_b32_e32 v22, v0
	v_mov_b32_e32 v23, v0
	v_mov_b32_e32 v32, v0
	v_mov_b32_e32 v33, v0
	v_mov_b32_e32 v34, v0
	v_mov_b32_e32 v35, v0
	v_mov_b32_e32 v36, v0
	v_mov_b32_e32 v37, v0
	v_mov_b32_e32 v38, v0
	v_mov_b32_e32 v39, v0
	v_mov_b32_e32 v48, v0
	v_mov_b32_e32 v49, v0
	v_mov_b32_e32 v50, v0
	v_mov_b32_e32 v51, v0
	v_mov_b32_e32 v52, v0
	v_mov_b32_e32 v53, v0
	v_mov_b32_e32 v54, v0
	v_mov_b32_e32 v55, v0
	v_mov_b32_e32 v8, v0
	v_mov_b32_e32 v9, v0
	v_mov_b32_e32 v10, v0
	v_mov_b32_e32 v11, v0
	v_mov_b32_e32 v12, v0
	v_mov_b32_e32 v13, v0
	v_mov_b32_e32 v14, v0
	v_mov_b32_e32 v15, v0
	v_mov_b32_e32 v24, v0
	v_mov_b32_e32 v25, v0
	v_mov_b32_e32 v26, v0
	v_mov_b32_e32 v27, v0
	v_mov_b32_e32 v28, v0
	v_mov_b32_e32 v29, v0
	v_mov_b32_e32 v30, v0
	v_mov_b32_e32 v31, v0
	v_mov_b32_e32 v40, v0
	v_mov_b32_e32 v41, v0
	v_mov_b32_e32 v42, v0
	v_mov_b32_e32 v43, v0
	v_mov_b32_e32 v44, v0
	v_mov_b32_e32 v45, v0
	v_mov_b32_e32 v46, v0
	v_mov_b32_e32 v47, v0
	v_mov_b32_e32 v56, v0
	v_mov_b32_e32 v57, v0
	v_mov_b32_e32 v58, v0
	v_mov_b32_e32 v59, v0
	v_mov_b32_e32 v60, v0
	v_mov_b32_e32 v61, v0
	v_mov_b32_e32 v62, v0
	v_mov_b32_e32 v63, v0
	v_mov_b32_e32 v64, v0
	v_mov_b32_e32 v65, v0
	v_mov_b32_e32 v66, v0
	v_mov_b32_e32 v67, v0
	v_mov_b32_e32 v68, v0
	v_mov_b32_e32 v69, v0
	v_mov_b32_e32 v70, v0
	v_mov_b32_e32 v71, v0
	v_mov_b32_e32 v80, v0
	v_mov_b32_e32 v81, v0
	v_mov_b32_e32 v82, v0
	v_mov_b32_e32 v83, v0
	v_mov_b32_e32 v84, v0
	v_mov_b32_e32 v85, v0
	v_mov_b32_e32 v86, v0
	v_mov_b32_e32 v87, v0
	v_mov_b32_e32 v102, v0
	v_mov_b32_e32 v103, v0
	v_mov_b32_e32 v104, v0
	v_mov_b32_e32 v105, v0
	v_mov_b32_e32 v106, v0
	v_mov_b32_e32 v107, v0
	v_mov_b32_e32 v108, v0
	v_mov_b32_e32 v109, v0
	v_mov_b32_e32 v118, v0
	v_mov_b32_e32 v119, v0
	v_mov_b32_e32 v120, v0
	v_mov_b32_e32 v121, v0
	v_mov_b32_e32 v122, v0
	v_mov_b32_e32 v123, v0
	v_mov_b32_e32 v124, v0
	v_mov_b32_e32 v125, v0
	v_mov_b32_e32 v72, v0
	v_mov_b32_e32 v73, v0
	v_mov_b32_e32 v74, v0
	v_mov_b32_e32 v75, v0
	v_mov_b32_e32 v76, v0
	v_mov_b32_e32 v77, v0
	v_mov_b32_e32 v78, v0
	v_mov_b32_e32 v79, v0
	v_mov_b32_e32 v88, v0
	v_mov_b32_e32 v89, v0
	v_mov_b32_e32 v90, v0
	v_mov_b32_e32 v91, v0
	v_mov_b32_e32 v92, v0
	v_mov_b32_e32 v93, v0
	v_mov_b32_e32 v94, v0
	v_mov_b32_e32 v95, v0
	v_mov_b32_e32 v110, v0
	v_mov_b32_e32 v111, v0
	v_mov_b32_e32 v112, v0
	v_mov_b32_e32 v113, v0
	v_mov_b32_e32 v114, v0
	v_mov_b32_e32 v115, v0
	v_mov_b32_e32 v116, v0
	v_mov_b32_e32 v117, v0
	v_mov_b32_e32 v134, v0
	v_mov_b32_e32 v135, v0
	v_mov_b32_e32 v136, v0
	v_mov_b32_e32 v137, v0
	v_mov_b32_e32 v138, v0
	v_mov_b32_e32 v139, v0
	v_mov_b32_e32 v140, v0
	v_mov_b32_e32 v141, v0
	s_cmp_gt_u32 s81, 0xff
	s_cbranch_scc0 .Lsp_403
	s_setprio 1
.Lsp_403:
.LBB0_403:
	s_add_u32 s52, s50, 0x100
	s_addc_u32 s53, s51, 0
	s_add_i32 s76, 0, 0x10000
	s_cmpk_eq_i32 s75, 0x54
	s_cselect_b32 s57, s45, s53
	s_cselect_b32 s56, s44, s52
	s_cselect_b32 s55, s47, s73
	s_cselect_b32 s54, s46, s72
	s_add_i32 s77, 0, 0x14000
	v_add_u32_e32 v146, s76, v233
	v_add_u32_e32 v162, s77, v233
	ds_read_b128 v[126:129], v146
	ds_read_b128 v[130:133], v146 offset:1024
	ds_read_b128 v[142:145], v146 offset:2048
	ds_read_b128 v[146:149], v146 offset:3072
	ds_read_b128 v[150:153], v162
	ds_read_b128 v[154:157], v162 offset:1024
	ds_read_b128 v[158:161], v162 offset:2048
	ds_read_b128 v[162:165], v162 offset:3072
	v_lshl_add_u64 v[210:211], s[50:51], 0, v[192:193]
	s_add_i32 m0, s60, 0xc000
	ds_read_b128 v[166:169], v236
	ds_read_b128 v[170:173], v236 offset:1024
	ds_read_b128 v[174:177], v236 offset:2048
	ds_read_b128 v[178:181], v236 offset:3072
	ds_read_b128 v[194:197], v236 offset:4096
	ds_read_b128 v[198:201], v236 offset:5120
	ds_read_b128 v[202:205], v236 offset:6144
	ds_read_b128 v[206:209], v236 offset:7168
	global_load_lds_dwordx4 v[210:211], off
	v_lshl_add_u64 v[210:211], s[50:51], 0, v[190:191]
	s_add_i32 m0, s60, 0xe000
	s_nop 0
	global_load_lds_dwordx4 v[210:211], off
	s_waitcnt vmcnt(8)
	s_waitcnt lgkmcnt(0)
	s_barrier
	v_mfma_f32_16x16x32_bf16 v[138:141], v[126:129], v[166:169], v[138:141]
	v_mfma_f32_16x16x32_bf16 v[134:137], v[142:145], v[166:169], v[134:137]
	v_mfma_f32_16x16x32_bf16 v[114:117], v[126:129], v[174:177], v[114:117]
	v_mfma_f32_16x16x32_bf16 v[110:113], v[142:145], v[174:177], v[110:113]
	v_mfma_f32_16x16x32_bf16 v[92:95], v[126:129], v[194:197], v[92:95]
	v_mfma_f32_16x16x32_bf16 v[88:91], v[142:145], v[194:197], v[88:91]
	v_mfma_f32_16x16x32_bf16 v[76:79], v[126:129], v[202:205], v[76:79]
	v_mfma_f32_16x16x32_bf16 v[72:75], v[142:145], v[202:205], v[72:75]
	v_mfma_f32_16x16x32_bf16 v[138:141], v[130:133], v[170:173], v[138:141]
	v_mfma_f32_16x16x32_bf16 v[134:137], v[146:149], v[170:173], v[134:137]
	v_mfma_f32_16x16x32_bf16 v[114:117], v[130:133], v[178:181], v[114:117]
	v_mfma_f32_16x16x32_bf16 v[110:113], v[146:149], v[178:181], v[110:113]
	v_mfma_f32_16x16x32_bf16 v[92:95], v[130:133], v[198:201], v[92:95]
	v_mfma_f32_16x16x32_bf16 v[88:91], v[146:149], v[198:201], v[88:91]
	v_mfma_f32_16x16x32_bf16 v[76:79], v[130:133], v[206:209], v[76:79]
	v_mfma_f32_16x16x32_bf16 v[72:75], v[146:149], v[206:209], v[72:75]
	v_mfma_f32_16x16x32_bf16 v[122:125], v[150:153], v[166:169], v[122:125]
	v_mfma_f32_16x16x32_bf16 v[118:121], v[158:161], v[166:169], v[118:121]
	v_mfma_f32_16x16x32_bf16 v[106:109], v[150:153], v[174:177], v[106:109]
	v_mfma_f32_16x16x32_bf16 v[102:105], v[158:161], v[174:177], v[102:105]
	v_mfma_f32_16x16x32_bf16 v[84:87], v[150:153], v[194:197], v[84:87]
	v_mfma_f32_16x16x32_bf16 v[80:83], v[158:161], v[194:197], v[80:83]
	v_mfma_f32_16x16x32_bf16 v[68:71], v[150:153], v[202:205], v[68:71]
	v_mfma_f32_16x16x32_bf16 v[64:67], v[158:161], v[202:205], v[64:67]
	v_mfma_f32_16x16x32_bf16 v[122:125], v[154:157], v[170:173], v[122:125]
	v_mfma_f32_16x16x32_bf16 v[118:121], v[162:165], v[170:173], v[118:121]
	v_mfma_f32_16x16x32_bf16 v[106:109], v[154:157], v[178:181], v[106:109]
	v_mfma_f32_16x16x32_bf16 v[102:105], v[162:165], v[178:181], v[102:105]
	v_mfma_f32_16x16x32_bf16 v[84:87], v[154:157], v[198:201], v[84:87]
	v_mfma_f32_16x16x32_bf16 v[80:83], v[162:165], v[198:201], v[80:83]
	v_mfma_f32_16x16x32_bf16 v[68:71], v[154:157], v[206:209], v[68:71]
	v_mfma_f32_16x16x32_bf16 v[64:67], v[162:165], v[206:209], v[64:67]
	s_barrier
; #define PG8_STAGE(bufoff, gbase, voff) do { _Pragma("unroll") for (int _i = 0; _i < 2; ++_i) \
;         __builtin_amdgcn_global_load_lds((const unsigned*)((const char*)(gbase) + (voff)[_i]), (PG8_LAS unsigned*)(lds + (bufoff) + ldsw + _i * 8192), 16, 0, 0); } while (0)
; #define PG8_LDA(dst, b, h) do { _Pragma("unroll") for (int m = 0; m < 4; ++m) _Pragma("unroll") for (int k = 0; k < 2; ++k) dst[m][k] = *(const PG8_LAS bf16x8*)(lds + PG8_SA(b, h) + aoff + m * 2048 + k * 1024); } while (0)
; #define PG8_LDB(dst, b, h) do { _Pragma("unroll") for (int n = 0; n < 2; ++n) _Pragma("unroll") for (int k = 0; k < 2; ++k) dst[n][k] = *(const PG8_LAS bf16x8*)(lds + PG8_SB(b, h) + boff + n * 2048 + k * 1024); } while (0)
; #define PG8_MMA(ai, bj, At, Bt) do { __builtin_amdgcn_s_setprio(1); _Pragma("unroll") for (int m = 0; m < 4; ++m) _Pragma("unroll") for (int n = 0; n < 2; ++n) _Pragma("unroll") for (int k = 0; k < 2; ++k) \
;         acc[ai][bj][m][n] = __builtin_amdgcn_mfma_f32_16x16x32_bf16(Bt[n][k], At[m][k], acc[ai][bj][m][n], 0, 0, 0); __builtin_amdgcn_s_setprio(0); } while (0)
; #define PG8_WAIT_V(n) asm volatile("s_waitcnt vmcnt(" #n ")" ::: "memory")
; #define PG8_WAIT_L(n) asm volatile("s_waitcnt lgkmcnt(" #n ")" ::: "memory")
; #define PG8_BAR __builtin_amdgcn_s_barrier()
; #define PG8_SCHED __builtin_amdgcn_sched_barrier(0)
; template <class Epi, class Sched, bool ALIGN_EPI = false, bool SP2 = false>
; __device__ __forceinline__ void gemm_phase(PG8_LAS unsigned char* lds, const Gemm g, const Sched& S, const Epi& E, const int tid) {
;     ...
;             PG8_LDA(At, 0, 1); PG8_STAGE(PG8_SB(0, 0), b2, voffB); PG8_STAGE(PG8_SB(0, 1), b2 + hstep, voffB); PG8_STAGE(PG8_SA(0, 0), a2, voffA);
;             PG8_WAIT_V(8); PG8_WAIT_L(0); PG8_BAR; PG8_MMA(1, 0, At, B0); PG8_MMA(1, 1, At, B1); PG8_BAR; PG8_SCHED;
;             PG8_LDB(B0, 1, 0); PG8_LDB(B1, 1, 1); PG8_SCHED; PG8_LDA(At, 1, 0); PG8_STAGE(PG8_SA(0, 1), a2 + hstep, voffA);
;             PG8_WAIT_V(8); PG8_WAIT_L(0); PG8_BAR; PG8_MMA(0, 0, At, B0); PG8_MMA(0, 1, At, B1); PG8_BAR; PG8_SCHED;
	s_add_i32 s50, s76, s59
	v_lshl_add_u64 v[210:211], s[54:55], 0, v[96:97]
	s_mov_b32 m0, s50
	ds_read_b128 v[166:169], v236 offset:16384
	ds_read_b128 v[170:173], v236 offset:17408
	ds_read_b128 v[174:177], v236 offset:18432
	ds_read_b128 v[178:181], v236 offset:19456
	ds_read_b128 v[194:197], v236 offset:20480
	ds_read_b128 v[198:201], v236 offset:21504
	ds_read_b128 v[202:205], v236 offset:22528
	ds_read_b128 v[206:209], v236 offset:23552
	global_load_lds_dwordx4 v[210:211], off
	s_add_i32 m0, s50, 0x2000
	s_add_u32 s50, s54, 0x160000
	v_lshl_add_u64 v[212:213], s[54:55], 0, v[98:99]
	s_addc_u32 s51, s55, 0
	s_add_i32 s76, s77, s59
	global_load_lds_dwordx4 v[212:213], off
	v_lshl_add_u64 v[214:215], s[50:51], 0, v[96:97]
	s_mov_b32 m0, s76
	v_lshl_add_u64 v[216:217], s[56:57], 0, v[186:187]
	global_load_lds_dwordx4 v[214:215], off
	v_lshl_add_u64 v[214:215], s[50:51], 0, v[98:99]
	s_add_i32 m0, s76, 0x2000
	s_nop 0
	global_load_lds_dwordx4 v[214:215], off
	v_lshl_add_u64 v[214:215], s[56:57], 0, v[188:189]
	s_mov_b32 m0, s60
	s_nop 0
	global_load_lds_dwordx4 v[214:215], off
	s_mov_b32 m0, s61
	s_nop 0
	global_load_lds_dwordx4 v[216:217], off
	s_waitcnt vmcnt(8)
	s_waitcnt lgkmcnt(0)
	s_barrier
	v_mfma_f32_16x16x32_bf16 v[60:63], v[126:129], v[166:169], v[60:63]
	v_mfma_f32_16x16x32_bf16 v[56:59], v[142:145], v[166:169], v[56:59]
	v_mfma_f32_16x16x32_bf16 v[44:47], v[126:129], v[174:177], v[44:47]
	v_mfma_f32_16x16x32_bf16 v[40:43], v[142:145], v[174:177], v[40:43]
	v_mfma_f32_16x16x32_bf16 v[28:31], v[126:129], v[194:197], v[28:31]
	v_mfma_f32_16x16x32_bf16 v[24:27], v[142:145], v[194:197], v[24:27]
	v_mfma_f32_16x16x32_bf16 v[12:15], v[126:129], v[202:205], v[12:15]
	v_mfma_f32_16x16x32_bf16 v[8:11], v[142:145], v[202:205], v[8:11]
	v_mfma_f32_16x16x32_bf16 v[60:63], v[130:133], v[170:173], v[60:63]
	v_mfma_f32_16x16x32_bf16 v[56:59], v[146:149], v[170:173], v[56:59]
	v_mfma_f32_16x16x32_bf16 v[44:47], v[130:133], v[178:181], v[44:47]
	v_mfma_f32_16x16x32_bf16 v[40:43], v[146:149], v[178:181], v[40:43]
	v_mfma_f32_16x16x32_bf16 v[28:31], v[130:133], v[198:201], v[28:31]
	v_mfma_f32_16x16x32_bf16 v[24:27], v[146:149], v[198:201], v[24:27]
	v_mfma_f32_16x16x32_bf16 v[12:15], v[130:133], v[206:209], v[12:15]
	v_mfma_f32_16x16x32_bf16 v[8:11], v[146:149], v[206:209], v[8:11]
	v_mfma_f32_16x16x32_bf16 v[52:55], v[150:153], v[166:169], v[52:55]
	v_mfma_f32_16x16x32_bf16 v[48:51], v[158:161], v[166:169], v[48:51]
	v_mfma_f32_16x16x32_bf16 v[36:39], v[150:153], v[174:177], v[36:39]
	v_mfma_f32_16x16x32_bf16 v[32:35], v[158:161], v[174:177], v[32:35]
	v_mfma_f32_16x16x32_bf16 v[20:23], v[150:153], v[194:197], v[20:23]
	v_mfma_f32_16x16x32_bf16 v[16:19], v[158:161], v[194:197], v[16:19]
	v_mfma_f32_16x16x32_bf16 v[4:7], v[150:153], v[202:205], v[4:7]
	v_mfma_f32_16x16x32_bf16 v[0:3], v[158:161], v[202:205], v[0:3]
	v_mfma_f32_16x16x32_bf16 v[52:55], v[154:157], v[170:173], v[52:55]
	v_mfma_f32_16x16x32_bf16 v[48:51], v[162:165], v[170:173], v[48:51]
	v_mfma_f32_16x16x32_bf16 v[36:39], v[154:157], v[178:181], v[36:39]
	v_mfma_f32_16x16x32_bf16 v[32:35], v[162:165], v[178:181], v[32:35]
	v_mfma_f32_16x16x32_bf16 v[20:23], v[154:157], v[198:201], v[20:23]
	v_mfma_f32_16x16x32_bf16 v[16:19], v[162:165], v[198:201], v[16:19]
	v_mfma_f32_16x16x32_bf16 v[4:7], v[154:157], v[206:209], v[4:7]
	v_mfma_f32_16x16x32_bf16 v[0:3], v[162:165], v[206:209], v[0:3]
	s_barrier
	s_add_i32 s76, 0, 0x18000
	s_add_i32 s77, 0, 0x1c000
	v_add_u32_e32 v146, s76, v233
	v_add_u32_e32 v162, s77, v233
	ds_read_b128 v[126:129], v146
	ds_read_b128 v[130:133], v146 offset:1024
	ds_read_b128 v[142:145], v146 offset:2048
	ds_read_b128 v[146:149], v146 offset:3072
	ds_read_b128 v[150:153], v162
	ds_read_b128 v[154:157], v162 offset:1024
	ds_read_b128 v[158:161], v162 offset:2048
	ds_read_b128 v[162:165], v162 offset:3072
	s_add_u32 s50, s56, 0x160000
	s_addc_u32 s51, s57, 0
	s_mov_b32 m0, s64
	v_lshl_add_u64 v[218:219], s[50:51], 0, v[188:189]
	ds_read_b128 v[166:169], v236 offset:32768
	ds_read_b128 v[170:173], v236 offset:33792
	ds_read_b128 v[174:177], v236 offset:34816
	ds_read_b128 v[178:181], v236 offset:35840
	ds_read_b128 v[194:197], v236 offset:36864
	ds_read_b128 v[198:201], v236 offset:37888
	ds_read_b128 v[202:205], v236 offset:38912
	ds_read_b128 v[206:209], v236 offset:39936
	global_load_lds_dwordx4 v[218:219], off
	v_lshl_add_u64 v[218:219], s[50:51], 0, v[186:187]
	s_mov_b32 m0, s65
	s_nop 0
	global_load_lds_dwordx4 v[218:219], off
	s_waitcnt vmcnt(8)
	s_waitcnt lgkmcnt(0)
	s_barrier
; #define PG8_STAGE(bufoff, gbase, voff) do { _Pragma("unroll") for (int _i = 0; _i < 2; ++_i) \
;         __builtin_amdgcn_global_load_lds((const unsigned*)((const char*)(gbase) + (voff)[_i]), (PG8_LAS unsigned*)(lds + (bufoff) + ldsw + _i * 8192), 16, 0, 0); } while (0)
; #define PG8_LDA(dst, b, h) do { _Pragma("unroll") for (int m = 0; m < 4; ++m) _Pragma("unroll") for (int k = 0; k < 2; ++k) dst[m][k] = *(const PG8_LAS bf16x8*)(lds + PG8_SA(b, h) + aoff + m * 2048 + k * 1024); } while (0)
; #define PG8_MMA(ai, bj, At, Bt) do { __builtin_amdgcn_s_setprio(1); _Pragma("unroll") for (int m = 0; m < 4; ++m) _Pragma("unroll") for (int n = 0; n < 2; ++n) _Pragma("unroll") for (int k = 0; k < 2; ++k) \
;         acc[ai][bj][m][n] = __builtin_amdgcn_mfma_f32_16x16x32_bf16(Bt[n][k], At[m][k], acc[ai][bj][m][n], 0, 0, 0); __builtin_amdgcn_s_setprio(0); } while (0)
; #define PG8_WAIT_V(n) asm volatile("s_waitcnt vmcnt(" #n ")" ::: "memory")
; #define PG8_WAIT_L(n) asm volatile("s_waitcnt lgkmcnt(" #n ")" ::: "memory")
; #define PG8_BAR __builtin_amdgcn_s_barrier()
; #define PG8_SCHED __builtin_amdgcn_sched_barrier(0)
; template <class Epi, class Sched, bool ALIGN_EPI = false, bool SP2 = false>
; __device__ __forceinline__ void gemm_phase(PG8_LAS unsigned char* lds, const Gemm g, const Sched& S, const Epi& E, const int tid) {
;     ...
;             PG8_WAIT_V(8); PG8_WAIT_L(0); PG8_BAR; PG8_MMA(0, 0, At, B0); PG8_MMA(0, 1, At, B1); PG8_BAR; PG8_SCHED;
;             PG8_LDA(At, 1, 1); PG8_STAGE(PG8_SB(1, 0), b3, voffB); PG8_STAGE(PG8_SB(1, 1), b3 + hstep, voffB); PG8_STAGE(PG8_SA(1, 0), a3, voffA);
;             PG8_WAIT_V(8); PG8_WAIT_L(0); PG8_BAR; PG8_MMA(1, 0, At, B0); PG8_MMA(1, 1, At, B1); PG8_BAR; PG8_SCHED;
	v_mfma_f32_16x16x32_bf16 v[138:141], v[126:129], v[166:169], v[138:141]
	v_mfma_f32_16x16x32_bf16 v[134:137], v[142:145], v[166:169], v[134:137]
	v_mfma_f32_16x16x32_bf16 v[114:117], v[126:129], v[174:177], v[114:117]
	v_mfma_f32_16x16x32_bf16 v[110:113], v[142:145], v[174:177], v[110:113]
	v_mfma_f32_16x16x32_bf16 v[92:95], v[126:129], v[194:197], v[92:95]
	v_mfma_f32_16x16x32_bf16 v[88:91], v[142:145], v[194:197], v[88:91]
	v_mfma_f32_16x16x32_bf16 v[76:79], v[126:129], v[202:205], v[76:79]
	v_mfma_f32_16x16x32_bf16 v[72:75], v[142:145], v[202:205], v[72:75]
	v_mfma_f32_16x16x32_bf16 v[138:141], v[130:133], v[170:173], v[138:141]
	v_mfma_f32_16x16x32_bf16 v[134:137], v[146:149], v[170:173], v[134:137]
	v_mfma_f32_16x16x32_bf16 v[114:117], v[130:133], v[178:181], v[114:117]
	v_mfma_f32_16x16x32_bf16 v[110:113], v[146:149], v[178:181], v[110:113]
	v_mfma_f32_16x16x32_bf16 v[92:95], v[130:133], v[198:201], v[92:95]
	v_mfma_f32_16x16x32_bf16 v[88:91], v[146:149], v[198:201], v[88:91]
	v_mfma_f32_16x16x32_bf16 v[76:79], v[130:133], v[206:209], v[76:79]
	v_mfma_f32_16x16x32_bf16 v[72:75], v[146:149], v[206:209], v[72:75]
	v_mfma_f32_16x16x32_bf16 v[122:125], v[150:153], v[166:169], v[122:125]
	v_mfma_f32_16x16x32_bf16 v[118:121], v[158:161], v[166:169], v[118:121]
	v_mfma_f32_16x16x32_bf16 v[106:109], v[150:153], v[174:177], v[106:109]
	v_mfma_f32_16x16x32_bf16 v[102:105], v[158:161], v[174:177], v[102:105]
	v_mfma_f32_16x16x32_bf16 v[84:87], v[150:153], v[194:197], v[84:87]
	v_mfma_f32_16x16x32_bf16 v[80:83], v[158:161], v[194:197], v[80:83]
	v_mfma_f32_16x16x32_bf16 v[68:71], v[150:153], v[202:205], v[68:71]
	v_mfma_f32_16x16x32_bf16 v[64:67], v[158:161], v[202:205], v[64:67]
	v_mfma_f32_16x16x32_bf16 v[122:125], v[154:157], v[170:173], v[122:125]
	v_mfma_f32_16x16x32_bf16 v[118:121], v[162:165], v[170:173], v[118:121]
	v_mfma_f32_16x16x32_bf16 v[106:109], v[154:157], v[178:181], v[106:109]
	v_mfma_f32_16x16x32_bf16 v[102:105], v[162:165], v[178:181], v[102:105]
	v_mfma_f32_16x16x32_bf16 v[84:87], v[154:157], v[198:201], v[84:87]
	v_mfma_f32_16x16x32_bf16 v[80:83], v[162:165], v[198:201], v[80:83]
	v_mfma_f32_16x16x32_bf16 v[68:71], v[154:157], v[206:209], v[68:71]
	v_mfma_f32_16x16x32_bf16 v[64:67], v[162:165], v[206:209], v[64:67]
	s_barrier
	s_add_i32 s50, s76, s59
	v_lshl_add_u64 v[210:211], v[210:211], 0, s[28:29]
	s_mov_b32 m0, s50
	ds_read_b128 v[166:169], v236 offset:49152
	ds_read_b128 v[170:173], v236 offset:50176
	ds_read_b128 v[174:177], v236 offset:51200
	ds_read_b128 v[178:181], v236 offset:52224
	ds_read_b128 v[194:197], v236 offset:53248
	ds_read_b128 v[198:201], v236 offset:54272
	ds_read_b128 v[202:205], v236 offset:55296
	ds_read_b128 v[206:209], v236 offset:56320
	global_load_lds_dwordx4 v[210:211], off
	s_add_i32 m0, s50, 0x2000
	s_add_u32 s50, s54, 0x160080
	v_lshl_add_u64 v[210:211], v[212:213], 0, s[28:29]
	s_addc_u32 s51, s55, 0
	s_add_i32 s54, s77, s59
	global_load_lds_dwordx4 v[210:211], off
	v_lshl_add_u64 v[210:211], s[50:51], 0, v[96:97]
	s_mov_b32 m0, s54
	s_nop 0
	global_load_lds_dwordx4 v[210:211], off
	v_lshl_add_u64 v[210:211], s[50:51], 0, v[98:99]
	s_add_i32 m0, s54, 0x2000
	s_nop 0
	global_load_lds_dwordx4 v[210:211], off
	v_lshl_add_u64 v[210:211], v[214:215], 0, s[28:29]
	s_mov_b32 m0, s63
	s_nop 0
	global_load_lds_dwordx4 v[210:211], off
	v_lshl_add_u64 v[210:211], v[216:217], 0, s[28:29]
	s_mov_b32 m0, s66
	s_nop 0
	global_load_lds_dwordx4 v[210:211], off
	s_waitcnt vmcnt(8)
	s_waitcnt lgkmcnt(0)
	s_barrier
	v_mfma_f32_16x16x32_bf16 v[60:63], v[126:129], v[166:169], v[60:63]
	v_mfma_f32_16x16x32_bf16 v[56:59], v[142:145], v[166:169], v[56:59]
	v_mfma_f32_16x16x32_bf16 v[44:47], v[126:129], v[174:177], v[44:47]
	v_mfma_f32_16x16x32_bf16 v[40:43], v[142:145], v[174:177], v[40:43]
	v_mfma_f32_16x16x32_bf16 v[28:31], v[126:129], v[194:197], v[28:31]
	v_mfma_f32_16x16x32_bf16 v[24:27], v[142:145], v[194:197], v[24:27]
	v_mfma_f32_16x16x32_bf16 v[12:15], v[126:129], v[202:205], v[12:15]
	v_mfma_f32_16x16x32_bf16 v[8:11], v[142:145], v[202:205], v[8:11]
	v_mfma_f32_16x16x32_bf16 v[60:63], v[130:133], v[170:173], v[60:63]
	v_mfma_f32_16x16x32_bf16 v[56:59], v[146:149], v[170:173], v[56:59]
	v_mfma_f32_16x16x32_bf16 v[44:47], v[130:133], v[178:181], v[44:47]
	v_mfma_f32_16x16x32_bf16 v[40:43], v[146:149], v[178:181], v[40:43]
	v_mfma_f32_16x16x32_bf16 v[28:31], v[130:133], v[198:201], v[28:31]
	v_mfma_f32_16x16x32_bf16 v[24:27], v[146:149], v[198:201], v[24:27]
	v_mfma_f32_16x16x32_bf16 v[12:15], v[130:133], v[206:209], v[12:15]
	v_mfma_f32_16x16x32_bf16 v[8:11], v[146:149], v[206:209], v[8:11]
	v_mfma_f32_16x16x32_bf16 v[52:55], v[150:153], v[166:169], v[52:55]
	v_mfma_f32_16x16x32_bf16 v[48:51], v[158:161], v[166:169], v[48:51]
	v_mfma_f32_16x16x32_bf16 v[36:39], v[150:153], v[174:177], v[36:39]
	v_mfma_f32_16x16x32_bf16 v[32:35], v[158:161], v[174:177], v[32:35]
	v_mfma_f32_16x16x32_bf16 v[20:23], v[150:153], v[194:197], v[20:23]
	v_mfma_f32_16x16x32_bf16 v[16:19], v[158:161], v[194:197], v[16:19]
	v_mfma_f32_16x16x32_bf16 v[4:7], v[150:153], v[202:205], v[4:7]
	v_mfma_f32_16x16x32_bf16 v[0:3], v[158:161], v[202:205], v[0:3]
	v_mfma_f32_16x16x32_bf16 v[52:55], v[154:157], v[170:173], v[52:55]
	v_mfma_f32_16x16x32_bf16 v[48:51], v[162:165], v[170:173], v[48:51]
	v_mfma_f32_16x16x32_bf16 v[36:39], v[154:157], v[178:181], v[36:39]
	v_mfma_f32_16x16x32_bf16 v[32:35], v[162:165], v[178:181], v[32:35]
	v_mfma_f32_16x16x32_bf16 v[20:23], v[154:157], v[198:201], v[20:23]
	v_mfma_f32_16x16x32_bf16 v[16:19], v[162:165], v[198:201], v[16:19]
	v_mfma_f32_16x16x32_bf16 v[4:7], v[154:157], v[206:209], v[4:7]
	v_mfma_f32_16x16x32_bf16 v[0:3], v[162:165], v[206:209], v[0:3]
	s_barrier
; #define PG8_GAS __attribute__((address_space(1)))
; __device__ __forceinline__ float e_x24(unsigned h16, unsigned l8) { return __uint_as_float(((h16 - (l8 >> 7)) << 16) | (l8 << 8)); }
;     __device__ __forceinline__ void operator()(const f32x4 (&acc)[2][2][4][2], const Unit& u, int wr, int wc, int fr, int fq) const {
;         const int row0 = u.pm * BM + wr * 64 + fr, col0 = u.pn * BM + wc * 32 + 8 * fq, lcol = u.pn * BM + (wc * 4 + fq) * 16;
; #pragma unroll
;         for (int ai = 0; ai < 2; ++ai) {
;             u32x4 L4[4], H4[4][2];
; #pragma unroll
;             for (int m = 0; m < 4; ++m) {
;                 const int row = row0 + ai * HALF + m * 16; const size_t off = (size_t)row * 2048 + col0, loff = (size_t)row * 2048 + lcol;
;                 L4[m] = *(const PG8_GAS u32x4*)(lin + loff); H4[m][0] = *(const PG8_GAS u32x4*)(hin + off); H4[m][1] = *(const PG8_GAS u32x4*)(hin + off + HALF);
;             }
; #pragma unroll
;             for (int m = 0; m < 4; ++m) {
;                 const int row = row0 + ai * HALF + m * 16; const size_t off = (size_t)row * 2048 + col0, loff = (size_t)row * 2048 + lcol; float ss = 0.f;
;                 const u32x4 l4 = L4[m];
;                 u32x4 lo4;
; #pragma unroll
;                 for (int bj = 0; bj < 2; ++bj) {
;                     const u32x4 h4 = H4[m][bj];
;                     u32x4 ho;
; #pragma unroll
;                     for (int j = 0; j < 4; ++j) {
;                         const unsigned lw = l4[2 * bj + (j >> 1)], lb0 = (lw >> (16 * (j & 1))) & 0xffu, lb1 = (lw >> (16 * (j & 1) + 8)) & 0xffu;
;                         const float x0 = e_x24(h4[j] & 0xffffu, lb0) + acc[ai][bj][m][j >> 1][2 * (j & 1)] * scale, x1 = e_x24(h4[j] >> 16, lb1) + acc[ai][bj][m][j >> 1][2 * (j & 1) + 1] * scale;
;                         const unsigned b0 = __float_as_uint(x0), b1 = __float_as_uint(x1);
;                         ho[j] = ((b0 + 0x8000u) >> 16) | ((b1 + 0x8000u) & 0xffff0000u);
	s_add_i32 s75, s75, 2
	s_add_u32 s72, s72, 0x100
	s_addc_u32 s73, s73, 0
	s_cmpk_gt_u32 s75, 0x55
	s_mov_b64 s[50:51], s[52:53]
	s_cbranch_scc0 .LBB0_403
	s_setprio 0
	v_and_b32_e32 v127, 64, v228
	v_xor_b32_e32 v126, 16, v228
	v_add_u32_e32 v127, 64, v127
	v_cmp_lt_i32_e32 vcc, v126, v127
	s_lshl_b32 s50, s70, 8
	v_lshl_add_u32 v198, s71, 8, v101
	v_cndmask_b32_e32 v126, v228, v126, vcc
	v_or_b32_e32 v194, s50, v235
	v_lshlrev_b32_e32 v238, 2, v126
	v_xor_b32_e32 v126, 32, v228
	v_or_b32_e32 v196, s50, v234
	v_ashrrev_i32_e32 v195, 31, v194
	v_cmp_lt_i32_e32 vcc, v126, v127
	v_ashrrev_i32_e32 v199, 31, v198
	v_ashrrev_i32_e32 v197, 31, v196
	v_cndmask_b32_e32 v126, v228, v126, vcc
	v_lshl_add_u64 v[202:203], s[34:35], 0, v[194:195]
	v_lshlrev_b64 v[216:217], 11, v[198:199]
	v_lshlrev_b32_e32 v237, 2, v126
	v_lshlrev_b64 v[218:219], 1, v[196:197]
	v_lshl_add_u64 v[126:127], v[202:203], 0, v[216:217]
	v_lshl_add_u64 v[200:201], s[30:31], 0, v[218:219]
	global_load_dwordx4 v[170:173], v[126:127], off
	v_lshlrev_b64 v[220:221], 12, v[198:199]
	v_lshl_add_u64 v[126:127], v[200:201], 0, v[220:221]
	global_load_dwordx4 v[178:181], v[126:127], off
	global_load_dwordx4 v[174:177], v[126:127], off offset:256
	v_or_b32_e32 v212, 16, v198
	v_ashrrev_i32_e32 v213, 31, v212
	v_lshlrev_b64 v[214:215], 11, v[212:213]
	v_lshl_add_u64 v[126:127], v[202:203], 0, v[214:215]
	v_or_b32_e32 v208, 32, v198
	global_load_dwordx4 v[158:161], v[126:127], off
	v_lshlrev_b64 v[126:127], 12, v[212:213]
	v_ashrrev_i32_e32 v209, 31, v208
	v_lshl_add_u64 v[126:127], v[200:201], 0, v[126:127]
	v_lshlrev_b64 v[210:211], 11, v[208:209]
	global_load_dwordx4 v[166:169], v[126:127], off
	global_load_dwordx4 v[162:165], v[126:127], off offset:256
	v_lshl_add_u64 v[126:127], v[202:203], 0, v[210:211]
	v_or_b32_e32 v204, 48, v198
	global_load_dwordx4 v[146:149], v[126:127], off
	v_lshlrev_b64 v[126:127], 12, v[208:209]
	v_ashrrev_i32_e32 v205, 31, v204
	v_lshl_add_u64 v[126:127], v[200:201], 0, v[126:127]
	v_lshlrev_b64 v[206:207], 11, v[204:205]
	v_lshlrev_b64 v[130:131], 12, v[204:205]
	global_load_dwordx4 v[154:157], v[126:127], off
	global_load_dwordx4 v[150:153], v[126:127], off offset:256
	v_lshl_add_u64 v[126:127], v[202:203], 0, v[206:207]
	v_lshl_add_u64 v[130:131], v[200:201], 0, v[130:131]
	global_load_dwordx4 v[126:129], v[126:127], off
	s_nop 0
	global_load_dwordx4 v[142:145], v[130:131], off
	s_nop 0
	global_load_dwordx4 v[130:133], v[130:131], off offset:256
	v_mov_b32_e32 v243, v136
	v_mov_b32_e32 v242, v140
	s_waitcnt vmcnt(0)
	v_lshrrev_b32_sdwa v222, v229, v171 dst_sel:DWORD dst_unused:UNUSED_PAD src0_sel:DWORD src1_sel:BYTE_0
	v_lshrrev_b32_sdwa v223, v229, v170 dst_sel:DWORD dst_unused:UNUSED_PAD src0_sel:DWORD src1_sel:BYTE_0
	v_sub_u32_sdwa v224, v178, v223 dst_sel:WORD_1 dst_unused:UNUSED_PAD src0_sel:DWORD src1_sel:DWORD
	v_sub_u32_sdwa v222, v180, v222 dst_sel:WORD_1 dst_unused:UNUSED_PAD src0_sel:DWORD src1_sel:DWORD
	v_lshlrev_b32_sdwa v223, v230, v171 dst_sel:DWORD dst_unused:UNUSED_PAD src0_sel:DWORD src1_sel:BYTE_0
	v_lshlrev_b32_sdwa v225, v230, v170 dst_sel:DWORD dst_unused:UNUSED_PAD src0_sel:DWORD src1_sel:BYTE_0
	v_or_b32_e32 v223, v222, v223
	v_or_b32_e32 v222, v224, v225
	v_mov_b32_e32 v224, v138
	v_mov_b32_e32 v225, v134
	v_pk_fma_f32 v[222:223], v[224:225], 0.5, v[222:223] op_sel_hi:[1,0,1]
	v_lshlrev_b32_e32 v224, 1, v170
	v_add_u32_e32 v134, 0x8000, v222
	v_lshrrev_b32_e32 v138, 16, v134
	v_lshlrev_b32_e32 v134, 1, v171
	v_and_b32_e32 v134, 0x10000, v134
	v_and_b32_e32 v224, 0x10000, v224
	v_sub_u32_e32 v134, v180, v134
	v_sub_u32_e32 v178, v178, v224
	v_and_b32_e32 v134, 0xffff0000, v134
	v_and_b32_e32 v178, 0xffff0000, v178
	v_and_b32_e32 v180, 0xff00, v171
	v_and_b32_e32 v224, 0xff00, v170
	v_or_b32_e32 v225, v134, v180
	v_or_b32_e32 v224, v178, v224
	v_mov_b32_e32 v134, v139
	v_pk_fma_f32 v[224:225], v[134:135], 0.5, v[224:225] op_sel_hi:[1,0,1]
	v_and_b32_sdwa v135, v171, s93 dst_sel:DWORD dst_unused:UNUSED_PAD src0_sel:WORD_1 src1_sel:DWORD
	v_and_b32_sdwa v178, v170, s93 dst_sel:DWORD dst_unused:UNUSED_PAD src0_sel:WORD_1 src1_sel:DWORD
	v_lshlrev_b32_sdwa v239, v231, v170 dst_sel:DWORD dst_unused:UNUSED_PAD src0_sel:DWORD src1_sel:BYTE_3
	v_lshlrev_b32_sdwa v136, v231, v171 dst_sel:DWORD dst_unused:UNUSED_PAD src0_sel:DWORD src1_sel:BYTE_3
	v_lshrrev_b32_e32 v180, 7, v178
	v_lshrrev_b32_e32 v240, 7, v135
	v_and_b32_e32 v136, 0x10000, v136
	v_and_b32_e32 v140, 0x10000, v239
	v_sub_u32_sdwa v180, v179, v180 dst_sel:WORD_1 dst_unused:UNUSED_PAD src0_sel:DWORD src1_sel:DWORD
	v_sub_u32_sdwa v240, v181, v240 dst_sel:WORD_1 dst_unused:UNUSED_PAD src0_sel:DWORD src1_sel:DWORD
	v_lshlrev_b32_e32 v135, 8, v135
	v_lshlrev_b32_e32 v178, 8, v178
	v_sub_u32_e32 v136, v181, v136
	v_sub_u32_e32 v140, v179, v140
	v_or_b32_e32 v241, v240, v135
	v_or_b32_e32 v240, v180, v178
	v_and_b32_e32 v136, 0xffff0000, v136
	v_and_b32_e32 v140, 0xffff0000, v140
	v_lshlrev_b32_sdwa v171, v230, v171 dst_sel:DWORD dst_unused:UNUSED_PAD src0_sel:DWORD src1_sel:BYTE_3
	v_lshlrev_b32_sdwa v170, v230, v170 dst_sel:DWORD dst_unused:UNUSED_PAD src0_sel:DWORD src1_sel:BYTE_3
	v_pk_fma_f32 v[240:241], v[242:243], 0.5, v[240:241] op_sel_hi:[1,0,1]
	v_or_b32_e32 v171, v136, v171
	v_or_b32_e32 v170, v140, v170
	v_mov_b32_e32 v136, v141
	v_add_u32_e32 v135, 0x8000, v240
	v_pk_fma_f32 v[140:141], v[136:137], 0.5, v[170:171] op_sel_hi:[1,0,1]
	v_lshrrev_b32_e32 v135, 16, v135
	v_add_u32_e32 v136, 0x8000, v140
	v_and_or_b32 v135, v136, s90, v135
	v_pk_mul_f32 v[136:137], v[140:141], v[140:141]
	v_add_u32_e32 v178, 0x8000, v141
	v_pk_fma_f32 v[170:171], v[240:241], v[240:241], v[136:137]
; #define PG8_GAS __attribute__((address_space(1)))
;     __device__ __forceinline__ void operator()(const f32x4 (&acc)[2][2][4][2], const Unit& u, int wr, int wc, int fr, int fq) const {
;     ...
;                         ho[j] = ((b0 + 0x8000u) >> 16) | ((b1 + 0x8000u) & 0xffff0000u);
;                         const unsigned nb = ((b0 >> 8) & 0xffu) | (b1 & 0xff00u);
;                         if ((j & 1) == 0) lo4[2 * bj + (j >> 1)] = nb; else lo4[2 * bj + (j >> 1)] |= nb << 16;
;                         ss += x0 * x0 + x1 * x1;
;                     }
;                     *(PG8_GAS u32x4*)(hout + off + bj * HALF) = ho;
;                 }
;                 *(PG8_GAS u32x4*)(lout + loff) = lo4;
;                 ss += __shfl_xor(ss, 16); ss += __shfl_xor(ss, 32);
;                 if (fq == 0) __hip_atomic_fetch_add((PG8_GAS unsigned long long*)(rowsq_out + row), (unsigned long long)(ss * 16777216.0f + 0.5f), __ATOMIC_RELAXED, __HIP_MEMORY_SCOPE_AGENT);
	v_add_u32_e32 v136, 0x8000, v223
	v_lshrrev_b32_e32 v136, 16, v136
	v_add_u32_e32 v137, 0x8000, v225
	v_and_or_b32 v136, v137, s90, v136
	v_add_u32_e32 v137, 0x8000, v241
	v_lshrrev_b32_e32 v137, 16, v137
	v_add_u32_e32 v134, 0x8000, v224
	v_and_or_b32 v137, v178, s90, v137
	v_lshl_add_u64 v[178:179], s[30:31], 0, v[220:221]
	v_and_or_b32 v134, v134, s90, v138
	v_lshl_add_u64 v[178:179], v[178:179], 0, v[218:219]
	global_store_dwordx4 v[178:179], v[134:137], off
	v_lshlrev_b32_sdwa v220, v231, v172 dst_sel:DWORD dst_unused:UNUSED_PAD src0_sel:DWORD src1_sel:BYTE_3
	v_mov_b32_e32 v219, v120
	v_lshrrev_b32_sdwa v134, v229, v173 dst_sel:DWORD dst_unused:UNUSED_PAD src0_sel:DWORD src1_sel:BYTE_0
	v_lshrrev_b32_sdwa v135, v229, v172 dst_sel:DWORD dst_unused:UNUSED_PAD src0_sel:DWORD src1_sel:BYTE_0
	v_sub_u32_sdwa v136, v174, v135 dst_sel:WORD_1 dst_unused:UNUSED_PAD src0_sel:DWORD src1_sel:DWORD
	v_sub_u32_sdwa v134, v176, v134 dst_sel:WORD_1 dst_unused:UNUSED_PAD src0_sel:DWORD src1_sel:DWORD
	v_lshlrev_b32_sdwa v135, v230, v173 dst_sel:DWORD dst_unused:UNUSED_PAD src0_sel:DWORD src1_sel:BYTE_0
	v_lshlrev_b32_sdwa v137, v230, v172 dst_sel:DWORD dst_unused:UNUSED_PAD src0_sel:DWORD src1_sel:BYTE_0
	v_or_b32_e32 v135, v134, v135
	v_or_b32_e32 v134, v136, v137
	v_mov_b32_e32 v136, v122
	v_mov_b32_e32 v137, v118
	v_pk_fma_f32 v[134:135], v[136:137], 0.5, v[134:135] op_sel_hi:[1,0,1]
	v_lshlrev_b32_e32 v122, 1, v172
	v_add_u32_e32 v118, 0x8000, v134
	v_lshrrev_b32_e32 v180, 16, v118
	v_lshlrev_b32_e32 v118, 1, v173
	v_and_b32_e32 v118, 0x10000, v118
	v_and_b32_e32 v122, 0x10000, v122
	v_sub_u32_e32 v118, v176, v118
	v_sub_u32_e32 v122, v174, v122
	v_and_b32_e32 v118, 0xffff0000, v118
	v_and_b32_e32 v122, 0xffff0000, v122
	v_and_b32_e32 v136, 0xff00, v173
	v_and_b32_e32 v174, 0xff00, v172
	v_or_b32_e32 v137, v118, v136
	v_or_b32_e32 v136, v122, v174
	v_mov_b32_e32 v118, v123
	v_pk_fma_f32 v[122:123], v[118:119], 0.5, v[136:137] op_sel_hi:[1,0,1]
	v_and_b32_sdwa v119, v173, s93 dst_sel:DWORD dst_unused:UNUSED_PAD src0_sel:WORD_1 src1_sel:DWORD
	v_add_u32_e32 v118, 0x8000, v122
	v_and_b32_sdwa v174, v172, s93 dst_sel:DWORD dst_unused:UNUSED_PAD src0_sel:WORD_1 src1_sel:DWORD
	v_lshlrev_b32_sdwa v120, v231, v173 dst_sel:DWORD dst_unused:UNUSED_PAD src0_sel:DWORD src1_sel:BYTE_3
	v_and_or_b32 v118, v118, s90, v180
	v_lshrrev_b32_e32 v176, 7, v174
	v_lshrrev_b32_e32 v180, 7, v119
	v_mov_b32_e32 v218, v124
	v_and_b32_e32 v120, 0x10000, v120
	v_and_b32_e32 v124, 0x10000, v220
	v_sub_u32_sdwa v176, v175, v176 dst_sel:WORD_1 dst_unused:UNUSED_PAD src0_sel:DWORD src1_sel:DWORD
	v_sub_u32_sdwa v180, v177, v180 dst_sel:WORD_1 dst_unused:UNUSED_PAD src0_sel:DWORD src1_sel:DWORD
	v_lshlrev_b32_e32 v119, 8, v119
	v_lshlrev_b32_e32 v174, 8, v174
	v_sub_u32_e32 v120, v177, v120
	v_sub_u32_e32 v124, v175, v124
	v_or_b32_e32 v181, v180, v119
	v_or_b32_e32 v180, v176, v174
	v_and_b32_e32 v120, 0xffff0000, v120
	v_and_b32_e32 v124, 0xffff0000, v124
	v_lshlrev_b32_sdwa v173, v230, v173 dst_sel:DWORD dst_unused:UNUSED_PAD src0_sel:DWORD src1_sel:BYTE_3
	v_lshlrev_b32_sdwa v172, v230, v172 dst_sel:DWORD dst_unused:UNUSED_PAD src0_sel:DWORD src1_sel:BYTE_3
	v_pk_fma_f32 v[180:181], v[218:219], 0.5, v[180:181] op_sel_hi:[1,0,1]
	v_or_b32_e32 v173, v120, v173
	v_or_b32_e32 v172, v124, v172
	v_mov_b32_e32 v120, v125
	v_add_u32_e32 v119, 0x8000, v180
	v_pk_fma_f32 v[124:125], v[120:121], 0.5, v[172:173] op_sel_hi:[1,0,1]
	v_lshrrev_b32_e32 v119, 16, v119
	v_add_u32_e32 v120, 0x8000, v124
	v_pk_mul_f32 v[138:139], v[224:225], v[224:225]
	v_pk_mul_f32 v[136:137], v[122:123], v[122:123]
	v_and_or_b32 v119, v120, s90, v119
	v_pk_mul_f32 v[120:121], v[124:125], v[124:125]
	v_pk_fma_f32 v[138:139], v[222:223], v[222:223], v[138:139]
	v_pk_fma_f32 v[136:137], v[134:135], v[134:135], v[136:137]
	v_pk_fma_f32 v[172:173], v[180:181], v[180:181], v[120:121]
	v_add_u32_e32 v120, 0x8000, v135
	v_lshrrev_b32_e32 v134, 8, v134
	v_lshrrev_b32_e32 v120, 16, v120
	v_add_u32_e32 v121, 0x8000, v123
	v_perm_b32 v122, v122, v134, s94
	v_add_f32_e32 v134, v138, v170
	v_and_or_b32 v120, v121, s90, v120
	v_add_u32_e32 v121, 0x8000, v181
	v_add_f32_e32 v134, v139, v134
	v_lshrrev_b32_e32 v121, 16, v121
	v_add_u32_e32 v174, 0x8000, v125
	v_add_f32_e32 v134, v171, v134
	v_and_or_b32 v121, v174, s90, v121
	v_lshrrev_b32_e32 v174, 8, v181
	v_lshrrev_b32_e32 v175, 8, v180
	v_add_f32_e32 v134, v136, v134
	v_lshrrev_b32_e32 v176, 8, v241
	v_lshrrev_b32_e32 v177, 8, v240
	v_perm_b32 v124, v124, v175, s94
	v_perm_b32 v125, v125, v174, s94
	v_lshrrev_b32_e32 v135, 8, v135
	v_lshrrev_b32_e32 v174, 8, v223
	v_lshrrev_b32_e32 v175, 8, v222
	v_add_f32_e32 v134, v172, v134
	v_perm_b32 v140, v140, v177, s94
	v_perm_b32 v141, v141, v176, s94
	v_perm_b32 v175, v224, v175, s94
	v_perm_b32 v174, v225, v174, s94
	v_perm_b32 v123, v123, v135, s94
	v_add_f32_e32 v134, v137, v134
	global_store_dwordx4 v[178:179], v[118:121], off offset:256
	v_lshl_or_b32 v125, v125, 16, v123
	v_lshl_or_b32 v124, v124, 16, v122
	v_lshl_add_u64 v[118:119], s[34:35], 0, v[216:217]
	v_lshl_or_b32 v123, v141, 16, v174
	v_lshl_or_b32 v122, v140, 16, v175
	v_add_f32_e32 v134, v173, v134
	v_lshl_add_u64 v[118:119], v[118:119], 0, v[194:195]
	global_store_dwordx4 v[118:119], v[122:125], off
	ds_bpermute_b32 v118, v238, v134
	s_waitcnt lgkmcnt(0)
	v_add_f32_e32 v118, v134, v118
	ds_bpermute_b32 v119, v237, v118
	s_and_saveexec_b64 s[50:51], s[40:41]
	s_cbranch_execz .LBB0_406
	s_waitcnt lgkmcnt(0)
	v_add_f32_e32 v118, v118, v119
	v_fma_f32 v118, v118, s80, 0.5
	v_trunc_f32_e32 v118, v118
	v_mul_f32_e32 v119, 0x2f800000, v118
	v_floor_f32_e32 v119, v119
	v_fmac_f32_e32 v118, 0xcf800000, v119
	v_cvt_u32_f32_e32 v118, v118
	v_cvt_u32_f32_e32 v119, v119
	v_lshl_add_u64 v[120:121], v[198:199], 3, s[48:49]
	global_atomic_add_x2 v[120:121], v[118:119], off

; #define PG8_STAGE(bufoff, gbase, voff) do { _Pragma("unroll") for (int _i = 0; _i < 2; ++_i) \
;         __builtin_amdgcn_global_load_lds((const unsigned*)((const char*)(gbase) + (voff)[_i]), (PG8_LAS unsigned*)(lds + (bufoff) + ldsw + _i * 8192), 16, 0, 0); } while (0)
; #define PG8_LDA(dst, b, h) do { _Pragma("unroll") for (int m = 0; m < 4; ++m) _Pragma("unroll") for (int k = 0; k < 2; ++k) dst[m][k] = *(const PG8_LAS bf16x8*)(lds + PG8_SA(b, h) + aoff + m * 2048 + k * 1024); } while (0)
; #define PG8_LDB(dst, b, h) do { _Pragma("unroll") for (int n = 0; n < 2; ++n) _Pragma("unroll") for (int k = 0; k < 2; ++k) dst[n][k] = *(const PG8_LAS bf16x8*)(lds + PG8_SB(b, h) + boff + n * 2048 + k * 1024); } while (0)
; #define PG8_MMA(ai, bj, At, Bt) do { __builtin_amdgcn_s_setprio(1); _Pragma("unroll") for (int m = 0; m < 4; ++m) _Pragma("unroll") for (int n = 0; n < 2; ++n) _Pragma("unroll") for (int k = 0; k < 2; ++k) \
;         acc[ai][bj][m][n] = __builtin_amdgcn_mfma_f32_16x16x32_bf16(Bt[n][k], At[m][k], acc[ai][bj][m][n], 0, 0, 0); __builtin_amdgcn_s_setprio(0); } while (0)
; #define PG8_WAIT_V(n) asm volatile("s_waitcnt vmcnt(" #n ")" ::: "memory")
; #define PG8_WAIT_L(n) asm volatile("s_waitcnt lgkmcnt(" #n ")" ::: "memory")
; #define PG8_BAR __builtin_amdgcn_s_barrier()
; #define PG8_SCHED __builtin_amdgcn_sched_barrier(0)
; template <class Epi, class Sched, bool ALIGN_EPI = false, bool SP2 = false>
; __device__ __forceinline__ void gemm_phase(PG8_LAS unsigned char* lds, const Gemm g, const Sched& S, const Epi& E, const int tid) {
;     ...
;             PG8_LDB(B0, 0, 0); PG8_LDB(B1, 0, 1); PG8_SCHED; PG8_LDA(At, 0, 0); PG8_STAGE(PG8_SA(1, 1), a1 + hstep, voffA);
;             PG8_WAIT_V(8); PG8_WAIT_L(0); PG8_BAR; PG8_MMA(0, 0, At, B0); PG8_MMA(0, 1, At, B1); PG8_BAR; PG8_SCHED;
;     ...
; #pragma unroll
;         for (int a = 0; a < 2; ++a)
; #pragma unroll
;             for (int b = 0; b < 2; ++b)
; #pragma unroll
;                 for (int m = 0; m < 4; ++m)
; #pragma unroll
;                     for (int n = 0; n < 2; ++n) acc[a][b][m][n] = (f32x4){0.f, 0.f, 0.f, 0.f};
.LBB0_487:
	s_ashr_i32 s53, s52, 31
	s_lshl_b64 s[54:55], s[52:53], 20
	s_add_u32 s54, s2, s54
	s_addc_u32 s55, s36, s55
	s_and_b64 s[56:57], s[40:41], exec
	s_cselect_b32 s53, s55, s59
	s_cselect_b32 s72, s54, s58
	s_ashr_i32 s51, s50, 31
	s_lshl_b64 s[56:57], s[50:51], 20
	s_add_u32 s56, s38, s56
	s_addc_u32 s57, s39, s57
	s_and_b64 s[60:61], s[40:41], exec
	s_cselect_b32 s51, s57, s43
	s_cselect_b32 s73, s56, s42
	s_cselect_b32 s100, 0, 0xf00
	s_add_u32 s72, s72, s100
	s_addc_u32 s53, s53, 0
	s_add_u32 s73, s73, s100
	s_addc_u32 s51, s51, 0
	s_add_u32 s75, s42, 0x100
	s_addc_u32 s76, s43, 0
	s_add_u32 s42, s58, 0x80080
	v_mov_b32_e32 v0, 0
	s_addc_u32 s43, s59, 0
	s_mov_b32 s77, -2
	v_mov_b32_e32 v1, v0
	v_mov_b32_e32 v2, v0
	v_mov_b32_e32 v3, v0
	v_mov_b32_e32 v12, v0
	v_mov_b32_e32 v13, v0
	v_mov_b32_e32 v14, v0
	v_mov_b32_e32 v15, v0
	v_mov_b32_e32 v16, v0
	v_mov_b32_e32 v17, v0
	v_mov_b32_e32 v18, v0
	v_mov_b32_e32 v19, v0
	v_mov_b32_e32 v28, v0
	v_mov_b32_e32 v29, v0
	v_mov_b32_e32 v30, v0
	v_mov_b32_e32 v31, v0
	v_mov_b32_e32 v32, v0
	v_mov_b32_e32 v33, v0
	v_mov_b32_e32 v34, v0
	v_mov_b32_e32 v35, v0
	v_mov_b32_e32 v44, v0
	v_mov_b32_e32 v45, v0
	v_mov_b32_e32 v46, v0
	v_mov_b32_e32 v47, v0
	v_mov_b32_e32 v48, v0
	v_mov_b32_e32 v49, v0
	v_mov_b32_e32 v50, v0
	v_mov_b32_e32 v51, v0
	v_mov_b32_e32 v60, v0
	v_mov_b32_e32 v61, v0
	v_mov_b32_e32 v62, v0
	v_mov_b32_e32 v63, v0
	v_mov_b32_e32 v4, v0
	v_mov_b32_e32 v5, v0
	v_mov_b32_e32 v6, v0
	v_mov_b32_e32 v7, v0
	v_mov_b32_e32 v8, v0
	v_mov_b32_e32 v9, v0
	v_mov_b32_e32 v10, v0
	v_mov_b32_e32 v11, v0
	v_mov_b32_e32 v20, v0
	v_mov_b32_e32 v21, v0
	v_mov_b32_e32 v22, v0
	v_mov_b32_e32 v23, v0
	v_mov_b32_e32 v24, v0
	v_mov_b32_e32 v25, v0
	v_mov_b32_e32 v26, v0
	v_mov_b32_e32 v27, v0
	v_mov_b32_e32 v36, v0
	v_mov_b32_e32 v37, v0
	v_mov_b32_e32 v38, v0
	v_mov_b32_e32 v39, v0
	v_mov_b32_e32 v40, v0
	v_mov_b32_e32 v41, v0
	v_mov_b32_e32 v42, v0
	v_mov_b32_e32 v43, v0
	v_mov_b32_e32 v52, v0
	v_mov_b32_e32 v53, v0
	v_mov_b32_e32 v54, v0
	v_mov_b32_e32 v55, v0
	v_mov_b32_e32 v56, v0
	v_mov_b32_e32 v57, v0
	v_mov_b32_e32 v58, v0
	v_mov_b32_e32 v59, v0
	v_mov_b32_e32 v64, v0
	v_mov_b32_e32 v65, v0
	v_mov_b32_e32 v66, v0
	v_mov_b32_e32 v67, v0
	v_mov_b32_e32 v76, v0
	v_mov_b32_e32 v77, v0
	v_mov_b32_e32 v78, v0
	v_mov_b32_e32 v79, v0
	v_mov_b32_e32 v80, v0
	v_mov_b32_e32 v81, v0
	v_mov_b32_e32 v82, v0
	v_mov_b32_e32 v83, v0
	v_mov_b32_e32 v92, v0
	v_mov_b32_e32 v93, v0
	v_mov_b32_e32 v94, v0
	v_mov_b32_e32 v95, v0
	v_mov_b32_e32 v102, v0
	v_mov_b32_e32 v103, v0
	v_mov_b32_e32 v104, v0
	v_mov_b32_e32 v105, v0
	v_mov_b32_e32 v114, v0
	v_mov_b32_e32 v115, v0
	v_mov_b32_e32 v116, v0
	v_mov_b32_e32 v117, v0
	v_mov_b32_e32 v126, v0
	v_mov_b32_e32 v127, v0
	v_mov_b32_e32 v128, v0
	v_mov_b32_e32 v129, v0
	v_mov_b32_e32 v130, v0
	v_mov_b32_e32 v131, v0
	v_mov_b32_e32 v132, v0
	v_mov_b32_e32 v133, v0
	v_mov_b32_e32 v68, v0
	v_mov_b32_e32 v69, v0
	v_mov_b32_e32 v70, v0
	v_mov_b32_e32 v71, v0
	v_mov_b32_e32 v72, v0
	v_mov_b32_e32 v73, v0
	v_mov_b32_e32 v74, v0
	v_mov_b32_e32 v75, v0
	v_mov_b32_e32 v84, v0
	v_mov_b32_e32 v85, v0
	v_mov_b32_e32 v86, v0
	v_mov_b32_e32 v87, v0
	v_mov_b32_e32 v88, v0
	v_mov_b32_e32 v89, v0
	v_mov_b32_e32 v90, v0
	v_mov_b32_e32 v91, v0
	v_mov_b32_e32 v106, v0
	v_mov_b32_e32 v107, v0
	v_mov_b32_e32 v108, v0
	v_mov_b32_e32 v109, v0
	v_mov_b32_e32 v110, v0
	v_mov_b32_e32 v111, v0
	v_mov_b32_e32 v112, v0
	v_mov_b32_e32 v113, v0
	v_mov_b32_e32 v118, v0
	v_mov_b32_e32 v119, v0
	v_mov_b32_e32 v120, v0
	v_mov_b32_e32 v121, v0
	v_mov_b32_e32 v122, v0
	v_mov_b32_e32 v123, v0
	v_mov_b32_e32 v124, v0
	v_mov_b32_e32 v125, v0
	s_cmp_gt_u32 s81, 0xff
	s_cbranch_scc0 .Lsp_488
	s_setprio 1
.Lsp_488:
.LBB0_488:
	s_add_u32 s58, s42, 0xfff80080
	s_addc_u32 s59, s43, -1
	s_add_i32 s78, 0, 0x10000
	s_cmp_eq_u32 s77, 28
	s_cselect_b32 s61, s53, s59
	s_cselect_b32 s60, s72, s58
	s_cselect_b32 s59, s51, s76
	s_cselect_b32 s58, s73, s75
	s_add_i32 s80, 0, 0x14000
	v_add_u32_e32 v156, s78, v163
	v_add_u32_e32 v160, s80, v163
	ds_read_b128 v[144:147], v156
	ds_read_b128 v[148:151], v156 offset:1024
	ds_read_b128 v[152:155], v156 offset:2048
	ds_read_b128 v[156:159], v156 offset:3072
	ds_read_b128 v[166:169], v160
	ds_read_b128 v[170:173], v160 offset:1024
	ds_read_b128 v[174:177], v160 offset:2048
	ds_read_b128 v[178:181], v160 offset:3072
	v_lshl_add_u64 v[160:161], s[42:43], 0, v[142:143]
	s_add_i32 m0, s63, 0xc000
	ds_read_b128 v[186:189], v165
	ds_read_b128 v[190:193], v165 offset:1024
	ds_read_b128 v[194:197], v165 offset:2048
	ds_read_b128 v[198:201], v165 offset:3072
	ds_read_b128 v[202:205], v165 offset:4096
	ds_read_b128 v[206:209], v165 offset:5120
	ds_read_b128 v[210:213], v165 offset:6144
	ds_read_b128 v[214:217], v165 offset:7168
	global_load_lds_dwordx4 v[160:161], off
	v_lshl_add_u64 v[160:161], s[42:43], 0, v[140:141]
	s_add_i32 m0, s63, 0xe000
	s_nop 0
	global_load_lds_dwordx4 v[160:161], off
	s_waitcnt vmcnt(8)
	s_waitcnt lgkmcnt(0)
	s_barrier
; #define PG8_STAGE(bufoff, gbase, voff) do { _Pragma("unroll") for (int _i = 0; _i < 2; ++_i) \
;         __builtin_amdgcn_global_load_lds((const unsigned*)((const char*)(gbase) + (voff)[_i]), (PG8_LAS unsigned*)(lds + (bufoff) + ldsw + _i * 8192), 16, 0, 0); } while (0)
; #define PG8_LDA(dst, b, h) do { _Pragma("unroll") for (int m = 0; m < 4; ++m) _Pragma("unroll") for (int k = 0; k < 2; ++k) dst[m][k] = *(const PG8_LAS bf16x8*)(lds + PG8_SA(b, h) + aoff + m * 2048 + k * 1024); } while (0)
; #define PG8_MMA(ai, bj, At, Bt) do { __builtin_amdgcn_s_setprio(1); _Pragma("unroll") for (int m = 0; m < 4; ++m) _Pragma("unroll") for (int n = 0; n < 2; ++n) _Pragma("unroll") for (int k = 0; k < 2; ++k) \
;         acc[ai][bj][m][n] = __builtin_amdgcn_mfma_f32_16x16x32_bf16(Bt[n][k], At[m][k], acc[ai][bj][m][n], 0, 0, 0); __builtin_amdgcn_s_setprio(0); } while (0)
; #define PG8_WAIT_V(n) asm volatile("s_waitcnt vmcnt(" #n ")" ::: "memory")
; #define PG8_WAIT_L(n) asm volatile("s_waitcnt lgkmcnt(" #n ")" ::: "memory")
; #define PG8_BAR __builtin_amdgcn_s_barrier()
; #define PG8_SCHED __builtin_amdgcn_sched_barrier(0)
; template <class Epi, class Sched, bool ALIGN_EPI = false, bool SP2 = false>
; __device__ __forceinline__ void gemm_phase(PG8_LAS unsigned char* lds, const Gemm g, const Sched& S, const Epi& E, const int tid) {
;     ...
;             PG8_WAIT_V(8); PG8_WAIT_L(0); PG8_BAR; PG8_MMA(0, 0, At, B0); PG8_MMA(0, 1, At, B1); PG8_BAR; PG8_SCHED;
;             PG8_LDA(At, 0, 1); PG8_STAGE(PG8_SB(0, 0), b2, voffB); PG8_STAGE(PG8_SB(0, 1), b2 + hstep, voffB); PG8_STAGE(PG8_SA(0, 0), a2, voffA);
;             PG8_WAIT_V(8); PG8_WAIT_L(0); PG8_BAR; PG8_MMA(1, 0, At, B0); PG8_MMA(1, 1, At, B1); PG8_BAR; PG8_SCHED;
	v_mfma_f32_16x16x32_bf16 v[122:125], v[144:147], v[186:189], v[122:125]
	v_mfma_f32_16x16x32_bf16 v[118:121], v[152:155], v[186:189], v[118:121]
	v_mfma_f32_16x16x32_bf16 v[110:113], v[144:147], v[194:197], v[110:113]
	v_mfma_f32_16x16x32_bf16 v[106:109], v[152:155], v[194:197], v[106:109]
	v_mfma_f32_16x16x32_bf16 v[88:91], v[144:147], v[202:205], v[88:91]
	v_mfma_f32_16x16x32_bf16 v[84:87], v[152:155], v[202:205], v[84:87]
	v_mfma_f32_16x16x32_bf16 v[72:75], v[144:147], v[210:213], v[72:75]
	v_mfma_f32_16x16x32_bf16 v[68:71], v[152:155], v[210:213], v[68:71]
	v_mfma_f32_16x16x32_bf16 v[122:125], v[148:151], v[190:193], v[122:125]
	v_mfma_f32_16x16x32_bf16 v[118:121], v[156:159], v[190:193], v[118:121]
	v_mfma_f32_16x16x32_bf16 v[110:113], v[148:151], v[198:201], v[110:113]
	v_mfma_f32_16x16x32_bf16 v[106:109], v[156:159], v[198:201], v[106:109]
	v_mfma_f32_16x16x32_bf16 v[88:91], v[148:151], v[206:209], v[88:91]
	v_mfma_f32_16x16x32_bf16 v[84:87], v[156:159], v[206:209], v[84:87]
	v_mfma_f32_16x16x32_bf16 v[72:75], v[148:151], v[214:217], v[72:75]
	v_mfma_f32_16x16x32_bf16 v[68:71], v[156:159], v[214:217], v[68:71]
	v_mfma_f32_16x16x32_bf16 v[130:133], v[166:169], v[186:189], v[130:133]
	v_mfma_f32_16x16x32_bf16 v[126:129], v[174:177], v[186:189], v[126:129]
	v_mfma_f32_16x16x32_bf16 v[114:117], v[166:169], v[194:197], v[114:117]
	v_mfma_f32_16x16x32_bf16 v[102:105], v[174:177], v[194:197], v[102:105]
	v_mfma_f32_16x16x32_bf16 v[92:95], v[166:169], v[202:205], v[92:95]
	v_mfma_f32_16x16x32_bf16 v[80:83], v[174:177], v[202:205], v[80:83]
	v_mfma_f32_16x16x32_bf16 v[76:79], v[166:169], v[210:213], v[76:79]
	v_mfma_f32_16x16x32_bf16 v[64:67], v[174:177], v[210:213], v[64:67]
	v_mfma_f32_16x16x32_bf16 v[130:133], v[170:173], v[190:193], v[130:133]
	v_mfma_f32_16x16x32_bf16 v[126:129], v[178:181], v[190:193], v[126:129]
	v_mfma_f32_16x16x32_bf16 v[114:117], v[170:173], v[198:201], v[114:117]
	v_mfma_f32_16x16x32_bf16 v[102:105], v[178:181], v[198:201], v[102:105]
	v_mfma_f32_16x16x32_bf16 v[92:95], v[170:173], v[206:209], v[92:95]
	v_mfma_f32_16x16x32_bf16 v[80:83], v[178:181], v[206:209], v[80:83]
	v_mfma_f32_16x16x32_bf16 v[76:79], v[170:173], v[214:217], v[76:79]
	v_mfma_f32_16x16x32_bf16 v[64:67], v[178:181], v[214:217], v[64:67]
	s_barrier
	s_add_i32 s78, s78, s62
	v_lshl_add_u64 v[160:161], s[58:59], 0, v[96:97]
	s_mov_b32 m0, s78
	ds_read_b128 v[186:189], v165 offset:16384
	ds_read_b128 v[190:193], v165 offset:17408
	ds_read_b128 v[194:197], v165 offset:18432
	ds_read_b128 v[198:201], v165 offset:19456
	ds_read_b128 v[202:205], v165 offset:20480
	ds_read_b128 v[206:209], v165 offset:21504
	ds_read_b128 v[210:213], v165 offset:22528
	ds_read_b128 v[214:217], v165 offset:23552
	global_load_lds_dwordx4 v[160:161], off
	s_add_i32 m0, s78, 0x2000
	s_add_u32 s78, s58, 0x80000
	v_lshl_add_u64 v[218:219], s[58:59], 0, v[98:99]
	s_addc_u32 s79, s59, 0
	s_add_i32 s80, s80, s62
	global_load_lds_dwordx4 v[218:219], off
	v_lshl_add_u64 v[220:221], s[78:79], 0, v[96:97]
	s_mov_b32 m0, s80
	v_lshl_add_u64 v[222:223], s[60:61], 0, v[134:135]
	global_load_lds_dwordx4 v[220:221], off
	v_lshl_add_u64 v[220:221], s[78:79], 0, v[98:99]
	s_add_i32 m0, s80, 0x2000
	s_nop 0
	global_load_lds_dwordx4 v[220:221], off
	v_lshl_add_u64 v[220:221], s[60:61], 0, v[136:137]
	s_mov_b32 m0, s63
	s_nop 0
	global_load_lds_dwordx4 v[220:221], off
	s_mov_b32 m0, s64
	s_nop 0
	global_load_lds_dwordx4 v[222:223], off
	s_waitcnt vmcnt(8)
	s_waitcnt lgkmcnt(0)
	s_barrier
	v_mfma_f32_16x16x32_bf16 v[56:59], v[144:147], v[186:189], v[56:59]
	v_mfma_f32_16x16x32_bf16 v[52:55], v[152:155], v[186:189], v[52:55]
	v_mfma_f32_16x16x32_bf16 v[40:43], v[144:147], v[194:197], v[40:43]
	v_mfma_f32_16x16x32_bf16 v[36:39], v[152:155], v[194:197], v[36:39]
	v_mfma_f32_16x16x32_bf16 v[24:27], v[144:147], v[202:205], v[24:27]
	v_mfma_f32_16x16x32_bf16 v[20:23], v[152:155], v[202:205], v[20:23]
	v_mfma_f32_16x16x32_bf16 v[8:11], v[144:147], v[210:213], v[8:11]
	v_mfma_f32_16x16x32_bf16 v[4:7], v[152:155], v[210:213], v[4:7]
	v_mfma_f32_16x16x32_bf16 v[56:59], v[148:151], v[190:193], v[56:59]
	v_mfma_f32_16x16x32_bf16 v[52:55], v[156:159], v[190:193], v[52:55]
	v_mfma_f32_16x16x32_bf16 v[40:43], v[148:151], v[198:201], v[40:43]
	v_mfma_f32_16x16x32_bf16 v[36:39], v[156:159], v[198:201], v[36:39]
	v_mfma_f32_16x16x32_bf16 v[24:27], v[148:151], v[206:209], v[24:27]
	v_mfma_f32_16x16x32_bf16 v[20:23], v[156:159], v[206:209], v[20:23]
	v_mfma_f32_16x16x32_bf16 v[8:11], v[148:151], v[214:217], v[8:11]
	v_mfma_f32_16x16x32_bf16 v[4:7], v[156:159], v[214:217], v[4:7]
	v_mfma_f32_16x16x32_bf16 v[60:63], v[166:169], v[186:189], v[60:63]
	v_mfma_f32_16x16x32_bf16 v[48:51], v[174:177], v[186:189], v[48:51]
	v_mfma_f32_16x16x32_bf16 v[44:47], v[166:169], v[194:197], v[44:47]
	v_mfma_f32_16x16x32_bf16 v[32:35], v[174:177], v[194:197], v[32:35]
	v_mfma_f32_16x16x32_bf16 v[28:31], v[166:169], v[202:205], v[28:31]
	v_mfma_f32_16x16x32_bf16 v[16:19], v[174:177], v[202:205], v[16:19]
	v_mfma_f32_16x16x32_bf16 v[12:15], v[166:169], v[210:213], v[12:15]
	v_mfma_f32_16x16x32_bf16 v[0:3], v[174:177], v[210:213], v[0:3]
	v_mfma_f32_16x16x32_bf16 v[60:63], v[170:173], v[190:193], v[60:63]
	v_mfma_f32_16x16x32_bf16 v[48:51], v[178:181], v[190:193], v[48:51]
	v_mfma_f32_16x16x32_bf16 v[44:47], v[170:173], v[198:201], v[44:47]
	v_mfma_f32_16x16x32_bf16 v[32:35], v[178:181], v[198:201], v[32:35]
	v_mfma_f32_16x16x32_bf16 v[28:31], v[170:173], v[206:209], v[28:31]
	v_mfma_f32_16x16x32_bf16 v[16:19], v[178:181], v[206:209], v[16:19]
	v_mfma_f32_16x16x32_bf16 v[12:15], v[170:173], v[214:217], v[12:15]
	v_mfma_f32_16x16x32_bf16 v[0:3], v[178:181], v[214:217], v[0:3]
	s_barrier
; #define PG8_STAGE(bufoff, gbase, voff) do { _Pragma("unroll") for (int _i = 0; _i < 2; ++_i) \
;         __builtin_amdgcn_global_load_lds((const unsigned*)((const char*)(gbase) + (voff)[_i]), (PG8_LAS unsigned*)(lds + (bufoff) + ldsw + _i * 8192), 16, 0, 0); } while (0)
; #define PG8_LDA(dst, b, h) do { _Pragma("unroll") for (int m = 0; m < 4; ++m) _Pragma("unroll") for (int k = 0; k < 2; ++k) dst[m][k] = *(const PG8_LAS bf16x8*)(lds + PG8_SA(b, h) + aoff + m * 2048 + k * 1024); } while (0)
; #define PG8_LDB(dst, b, h) do { _Pragma("unroll") for (int n = 0; n < 2; ++n) _Pragma("unroll") for (int k = 0; k < 2; ++k) dst[n][k] = *(const PG8_LAS bf16x8*)(lds + PG8_SB(b, h) + boff + n * 2048 + k * 1024); } while (0)
; #define PG8_MMA(ai, bj, At, Bt) do { __builtin_amdgcn_s_setprio(1); _Pragma("unroll") for (int m = 0; m < 4; ++m) _Pragma("unroll") for (int n = 0; n < 2; ++n) _Pragma("unroll") for (int k = 0; k < 2; ++k) \
;         acc[ai][bj][m][n] = __builtin_amdgcn_mfma_f32_16x16x32_bf16(Bt[n][k], At[m][k], acc[ai][bj][m][n], 0, 0, 0); __builtin_amdgcn_s_setprio(0); } while (0)
; #define PG8_WAIT_V(n) asm volatile("s_waitcnt vmcnt(" #n ")" ::: "memory")
; #define PG8_WAIT_L(n) asm volatile("s_waitcnt lgkmcnt(" #n ")" ::: "memory")
; #define PG8_BAR __builtin_amdgcn_s_barrier()
; #define PG8_SCHED __builtin_amdgcn_sched_barrier(0)
; template <class Epi, class Sched, bool ALIGN_EPI = false, bool SP2 = false>
; __device__ __forceinline__ void gemm_phase(PG8_LAS unsigned char* lds, const Gemm g, const Sched& S, const Epi& E, const int tid) {
;     ...
;             PG8_LDB(B0, 1, 0); PG8_LDB(B1, 1, 1); PG8_SCHED; PG8_LDA(At, 1, 0); PG8_STAGE(PG8_SA(0, 1), a2 + hstep, voffA);
;             PG8_WAIT_V(8); PG8_WAIT_L(0); PG8_BAR; PG8_MMA(0, 0, At, B0); PG8_MMA(0, 1, At, B1); PG8_BAR; PG8_SCHED;
	s_add_i32 s78, 0, 0x18000
	s_add_i32 s79, 0, 0x1c000
	v_add_u32_e32 v156, s78, v163
	v_add_u32_e32 v162, s79, v163
	ds_read_b128 v[144:147], v156
	ds_read_b128 v[148:151], v156 offset:1024
	ds_read_b128 v[152:155], v156 offset:2048
	ds_read_b128 v[156:159], v156 offset:3072
	ds_read_b128 v[166:169], v162
	ds_read_b128 v[170:173], v162 offset:1024
	ds_read_b128 v[174:177], v162 offset:2048
	ds_read_b128 v[178:181], v162 offset:3072
	s_add_u32 s60, s60, 0x80000
	s_addc_u32 s61, s61, 0
	s_mov_b32 m0, s65
	v_lshl_add_u64 v[224:225], s[60:61], 0, v[136:137]
	ds_read_b128 v[186:189], v165 offset:32768
	ds_read_b128 v[190:193], v165 offset:33792
	ds_read_b128 v[194:197], v165 offset:34816
	ds_read_b128 v[198:201], v165 offset:35840
	ds_read_b128 v[202:205], v165 offset:36864
	ds_read_b128 v[206:209], v165 offset:37888
	ds_read_b128 v[210:213], v165 offset:38912
	ds_read_b128 v[214:217], v165 offset:39936
	global_load_lds_dwordx4 v[224:225], off
	v_lshl_add_u64 v[224:225], s[60:61], 0, v[134:135]
	s_mov_b32 m0, s66
	s_nop 0
	global_load_lds_dwordx4 v[224:225], off
	s_waitcnt vmcnt(8)
	s_waitcnt lgkmcnt(0)
	s_barrier
	v_mfma_f32_16x16x32_bf16 v[122:125], v[144:147], v[186:189], v[122:125]
	v_mfma_f32_16x16x32_bf16 v[118:121], v[152:155], v[186:189], v[118:121]
	v_mfma_f32_16x16x32_bf16 v[110:113], v[144:147], v[194:197], v[110:113]
	v_mfma_f32_16x16x32_bf16 v[106:109], v[152:155], v[194:197], v[106:109]
	v_mfma_f32_16x16x32_bf16 v[88:91], v[144:147], v[202:205], v[88:91]
	v_mfma_f32_16x16x32_bf16 v[84:87], v[152:155], v[202:205], v[84:87]
	v_mfma_f32_16x16x32_bf16 v[72:75], v[144:147], v[210:213], v[72:75]
	v_mfma_f32_16x16x32_bf16 v[68:71], v[152:155], v[210:213], v[68:71]
	v_mfma_f32_16x16x32_bf16 v[122:125], v[148:151], v[190:193], v[122:125]
	v_mfma_f32_16x16x32_bf16 v[118:121], v[156:159], v[190:193], v[118:121]
	v_mfma_f32_16x16x32_bf16 v[110:113], v[148:151], v[198:201], v[110:113]
	v_mfma_f32_16x16x32_bf16 v[106:109], v[156:159], v[198:201], v[106:109]
	v_mfma_f32_16x16x32_bf16 v[88:91], v[148:151], v[206:209], v[88:91]
	v_mfma_f32_16x16x32_bf16 v[84:87], v[156:159], v[206:209], v[84:87]
	v_mfma_f32_16x16x32_bf16 v[72:75], v[148:151], v[214:217], v[72:75]
	v_mfma_f32_16x16x32_bf16 v[68:71], v[156:159], v[214:217], v[68:71]
	v_mfma_f32_16x16x32_bf16 v[130:133], v[166:169], v[186:189], v[130:133]
	v_mfma_f32_16x16x32_bf16 v[126:129], v[174:177], v[186:189], v[126:129]
	v_mfma_f32_16x16x32_bf16 v[114:117], v[166:169], v[194:197], v[114:117]
	v_mfma_f32_16x16x32_bf16 v[102:105], v[174:177], v[194:197], v[102:105]
	v_mfma_f32_16x16x32_bf16 v[92:95], v[166:169], v[202:205], v[92:95]
	v_mfma_f32_16x16x32_bf16 v[80:83], v[174:177], v[202:205], v[80:83]
	v_mfma_f32_16x16x32_bf16 v[76:79], v[166:169], v[210:213], v[76:79]
	v_mfma_f32_16x16x32_bf16 v[64:67], v[174:177], v[210:213], v[64:67]
	v_mfma_f32_16x16x32_bf16 v[130:133], v[170:173], v[190:193], v[130:133]
	v_mfma_f32_16x16x32_bf16 v[126:129], v[178:181], v[190:193], v[126:129]
	v_mfma_f32_16x16x32_bf16 v[114:117], v[170:173], v[198:201], v[114:117]
	v_mfma_f32_16x16x32_bf16 v[102:105], v[178:181], v[198:201], v[102:105]
	v_mfma_f32_16x16x32_bf16 v[92:95], v[170:173], v[206:209], v[92:95]
	v_mfma_f32_16x16x32_bf16 v[80:83], v[178:181], v[206:209], v[80:83]
	v_mfma_f32_16x16x32_bf16 v[76:79], v[170:173], v[214:217], v[76:79]
	v_mfma_f32_16x16x32_bf16 v[64:67], v[178:181], v[214:217], v[64:67]
	s_barrier
; #define PG8_STAGE(bufoff, gbase, voff) do { _Pragma("unroll") for (int _i = 0; _i < 2; ++_i) \
;         __builtin_amdgcn_global_load_lds((const unsigned*)((const char*)(gbase) + (voff)[_i]), (PG8_LAS unsigned*)(lds + (bufoff) + ldsw + _i * 8192), 16, 0, 0); } while (0)
; #define PG8_LDA(dst, b, h) do { _Pragma("unroll") for (int m = 0; m < 4; ++m) _Pragma("unroll") for (int k = 0; k < 2; ++k) dst[m][k] = *(const PG8_LAS bf16x8*)(lds + PG8_SA(b, h) + aoff + m * 2048 + k * 1024); } while (0)
; #define PG8_MMA(ai, bj, At, Bt) do { __builtin_amdgcn_s_setprio(1); _Pragma("unroll") for (int m = 0; m < 4; ++m) _Pragma("unroll") for (int n = 0; n < 2; ++n) _Pragma("unroll") for (int k = 0; k < 2; ++k) \
;         acc[ai][bj][m][n] = __builtin_amdgcn_mfma_f32_16x16x32_bf16(Bt[n][k], At[m][k], acc[ai][bj][m][n], 0, 0, 0); __builtin_amdgcn_s_setprio(0); } while (0)
; #define PG8_WAIT_V(n) asm volatile("s_waitcnt vmcnt(" #n ")" ::: "memory")
; #define PG8_WAIT_L(n) asm volatile("s_waitcnt lgkmcnt(" #n ")" ::: "memory")
; #define PG8_BAR __builtin_amdgcn_s_barrier()
; #define PG8_SCHED __builtin_amdgcn_sched_barrier(0)
; template <class Epi, class Sched, bool ALIGN_EPI = false, bool SP2 = false>
; __device__ __forceinline__ void gemm_phase(PG8_LAS unsigned char* lds, const Gemm g, const Sched& S, const Epi& E, const int tid) {
;     ...
;             PG8_LDA(At, 1, 1); PG8_STAGE(PG8_SB(1, 0), b3, voffB); PG8_STAGE(PG8_SB(1, 1), b3 + hstep, voffB); PG8_STAGE(PG8_SA(1, 0), a3, voffA);
;             PG8_WAIT_V(8); PG8_WAIT_L(0); PG8_BAR; PG8_MMA(1, 0, At, B0); PG8_MMA(1, 1, At, B1); PG8_BAR; PG8_SCHED;
;     ...
;         if constexpr (ALIGN_EPI) { if (wr == 0) PG8_BAR; }
	s_add_i32 s60, s78, s62
	v_lshl_add_u64 v[160:161], v[160:161], 0, s[28:29]
	s_mov_b32 m0, s60
	ds_read_b128 v[186:189], v165 offset:49152
	ds_read_b128 v[190:193], v165 offset:50176
	ds_read_b128 v[194:197], v165 offset:51200
	ds_read_b128 v[198:201], v165 offset:52224
	ds_read_b128 v[202:205], v165 offset:53248
	ds_read_b128 v[206:209], v165 offset:54272
	ds_read_b128 v[210:213], v165 offset:55296
	ds_read_b128 v[214:217], v165 offset:56320
	global_load_lds_dwordx4 v[160:161], off
	s_add_i32 m0, s60, 0x2000
	s_add_u32 s58, s58, 0x80080
	v_lshl_add_u64 v[160:161], v[218:219], 0, s[28:29]
	s_addc_u32 s59, s59, 0
	s_add_i32 s60, s79, s62
	global_load_lds_dwordx4 v[160:161], off
	v_lshl_add_u64 v[160:161], s[58:59], 0, v[96:97]
	s_mov_b32 m0, s60
	s_nop 0
	global_load_lds_dwordx4 v[160:161], off
	v_lshl_add_u64 v[160:161], s[58:59], 0, v[98:99]
	s_add_i32 m0, s60, 0x2000
	s_nop 0
	global_load_lds_dwordx4 v[160:161], off
	v_lshl_add_u64 v[160:161], v[220:221], 0, s[28:29]
	s_mov_b32 m0, s67
	s_nop 0
	global_load_lds_dwordx4 v[160:161], off
	v_lshl_add_u64 v[160:161], v[222:223], 0, s[28:29]
	s_mov_b32 m0, s68
	s_nop 0
	global_load_lds_dwordx4 v[160:161], off
	s_waitcnt vmcnt(8)
	s_waitcnt lgkmcnt(0)
	s_barrier
	v_mfma_f32_16x16x32_bf16 v[56:59], v[144:147], v[186:189], v[56:59]
	v_mfma_f32_16x16x32_bf16 v[52:55], v[152:155], v[186:189], v[52:55]
	v_mfma_f32_16x16x32_bf16 v[40:43], v[144:147], v[194:197], v[40:43]
	v_mfma_f32_16x16x32_bf16 v[36:39], v[152:155], v[194:197], v[36:39]
	v_mfma_f32_16x16x32_bf16 v[24:27], v[144:147], v[202:205], v[24:27]
	v_mfma_f32_16x16x32_bf16 v[20:23], v[152:155], v[202:205], v[20:23]
	v_mfma_f32_16x16x32_bf16 v[8:11], v[144:147], v[210:213], v[8:11]
	v_mfma_f32_16x16x32_bf16 v[4:7], v[152:155], v[210:213], v[4:7]
	v_mfma_f32_16x16x32_bf16 v[56:59], v[148:151], v[190:193], v[56:59]
	v_mfma_f32_16x16x32_bf16 v[52:55], v[156:159], v[190:193], v[52:55]
	v_mfma_f32_16x16x32_bf16 v[40:43], v[148:151], v[198:201], v[40:43]
	v_mfma_f32_16x16x32_bf16 v[36:39], v[156:159], v[198:201], v[36:39]
	v_mfma_f32_16x16x32_bf16 v[24:27], v[148:151], v[206:209], v[24:27]
	v_mfma_f32_16x16x32_bf16 v[20:23], v[156:159], v[206:209], v[20:23]
	v_mfma_f32_16x16x32_bf16 v[8:11], v[148:151], v[214:217], v[8:11]
	v_mfma_f32_16x16x32_bf16 v[4:7], v[156:159], v[214:217], v[4:7]
	v_mfma_f32_16x16x32_bf16 v[60:63], v[166:169], v[186:189], v[60:63]
	v_mfma_f32_16x16x32_bf16 v[48:51], v[174:177], v[186:189], v[48:51]
	v_mfma_f32_16x16x32_bf16 v[44:47], v[166:169], v[194:197], v[44:47]
	v_mfma_f32_16x16x32_bf16 v[32:35], v[174:177], v[194:197], v[32:35]
	v_mfma_f32_16x16x32_bf16 v[28:31], v[166:169], v[202:205], v[28:31]
	v_mfma_f32_16x16x32_bf16 v[16:19], v[174:177], v[202:205], v[16:19]
	v_mfma_f32_16x16x32_bf16 v[12:15], v[166:169], v[210:213], v[12:15]
	v_mfma_f32_16x16x32_bf16 v[0:3], v[174:177], v[210:213], v[0:3]
	v_mfma_f32_16x16x32_bf16 v[60:63], v[170:173], v[190:193], v[60:63]
	v_mfma_f32_16x16x32_bf16 v[48:51], v[178:181], v[190:193], v[48:51]
	v_mfma_f32_16x16x32_bf16 v[44:47], v[170:173], v[198:201], v[44:47]
	v_mfma_f32_16x16x32_bf16 v[32:35], v[178:181], v[198:201], v[32:35]
	v_mfma_f32_16x16x32_bf16 v[28:31], v[170:173], v[206:209], v[28:31]
	v_mfma_f32_16x16x32_bf16 v[16:19], v[178:181], v[206:209], v[16:19]
	v_mfma_f32_16x16x32_bf16 v[12:15], v[170:173], v[214:217], v[12:15]
	v_mfma_f32_16x16x32_bf16 v[0:3], v[178:181], v[214:217], v[0:3]
	s_barrier
	s_add_i32 s77, s77, 2
	s_add_u32 s75, s75, 0x100
	s_addc_u32 s76, s76, 0
	s_add_u32 s42, s42, 0x100
	s_addc_u32 s43, s43, 0
	s_cmp_gt_u32 s77, 29
	s_cbranch_scc0 .LBB0_488
	s_setprio 0
	s_and_b64 vcc, exec, s[46:47]
	s_cbranch_vccz .LBB0_491
	s_barrier

; #define PG8_STAGE(bufoff, gbase, voff) do { _Pragma("unroll") for (int _i = 0; _i < 2; ++_i) \
;         __builtin_amdgcn_global_load_lds((const unsigned*)((const char*)(gbase) + (voff)[_i]), (PG8_LAS unsigned*)(lds + (bufoff) + ldsw + _i * 8192), 16, 0, 0); } while (0)
; #define PG8_LDA(dst, b, h) do { _Pragma("unroll") for (int m = 0; m < 4; ++m) _Pragma("unroll") for (int k = 0; k < 2; ++k) dst[m][k] = *(const PG8_LAS bf16x8*)(lds + PG8_SA(b, h) + aoff + m * 2048 + k * 1024); } while (0)
; #define PG8_LDB(dst, b, h) do { _Pragma("unroll") for (int n = 0; n < 2; ++n) _Pragma("unroll") for (int k = 0; k < 2; ++k) dst[n][k] = *(const PG8_LAS bf16x8*)(lds + PG8_SB(b, h) + boff + n * 2048 + k * 1024); } while (0)
; #define PG8_MMA(ai, bj, At, Bt) do { __builtin_amdgcn_s_setprio(1); _Pragma("unroll") for (int m = 0; m < 4; ++m) _Pragma("unroll") for (int n = 0; n < 2; ++n) _Pragma("unroll") for (int k = 0; k < 2; ++k) \
;         acc[ai][bj][m][n] = __builtin_amdgcn_mfma_f32_16x16x32_bf16(Bt[n][k], At[m][k], acc[ai][bj][m][n], 0, 0, 0); __builtin_amdgcn_s_setprio(0); } while (0)
; #define PG8_WAIT_V(n) asm volatile("s_waitcnt vmcnt(" #n ")" ::: "memory")
; #define PG8_WAIT_L(n) asm volatile("s_waitcnt lgkmcnt(" #n ")" ::: "memory")
; #define PG8_BAR __builtin_amdgcn_s_barrier()
; #define PG8_SCHED __builtin_amdgcn_sched_barrier(0)
; template <class Epi, class Sched, bool ALIGN_EPI = false, bool SP2 = false>
; __device__ __forceinline__ void gemm_phase(PG8_LAS unsigned char* lds, const Gemm g, const Sched& S, const Epi& E, const int tid) {
;     ...
;             PG8_LDB(B0, 0, 0); PG8_LDB(B1, 0, 1); PG8_SCHED; PG8_LDA(At, 0, 0); PG8_STAGE(PG8_SA(1, 1), a1 + hstep, voffA);
;             PG8_WAIT_V(8); PG8_WAIT_L(0); PG8_BAR; PG8_MMA(0, 0, At, B0); PG8_MMA(0, 1, At, B1); PG8_BAR; PG8_SCHED;
;     ...
; #pragma unroll
;         for (int a = 0; a < 2; ++a)
; #pragma unroll
;             for (int b = 0; b < 2; ++b)
; #pragma unroll
;                 for (int m = 0; m < 4; ++m)
; #pragma unroll
;                     for (int n = 0; n < 2; ++n) acc[a][b][m][n] = (f32x4){0.f, 0.f, 0.f, 0.f};
.LBB0_1198:
	s_ashr_i32 s49, s48, 31
	v_cmp_lt_i64_e32 vcc, s[50:51], v[244:245]
	s_lshl_b64 s[50:51], s[48:49], 20
	s_add_u32 s50, s36, s50
	s_addc_u32 s51, s38, s51
	s_and_b64 s[52:53], vcc, exec
	s_cselect_b32 s49, s51, s57
	s_cselect_b32 s71, s50, s56
	s_ashr_i32 s47, s46, 31
	s_lshl_b64 s[52:53], s[46:47], 20
	s_add_u32 s52, s39, s52
	s_addc_u32 s53, s60, s53
	s_and_b64 s[58:59], vcc, exec
	s_cselect_b32 s47, s53, s55
	s_cselect_b32 s72, s52, s54
	s_cselect_b32 s100, 0, 0xf00
	s_add_u32 s71, s71, s100
	s_addc_u32 s49, s49, 0
	s_add_u32 s72, s72, s100
	s_addc_u32 s47, s47, 0
	s_add_u32 s73, s54, 0x100
	s_addc_u32 s75, s55, 0
	s_add_u32 s54, s56, 0x80080
	v_mov_b32_e32 v0, 0
	s_addc_u32 s55, s57, 0
	s_mov_b32 s76, -2
	s_waitcnt lgkmcnt(0)
	v_mov_b32_e32 v1, v0
	v_mov_b32_e32 v2, v0
	v_mov_b32_e32 v3, v0
	v_mov_b32_e32 v4, v0
	v_mov_b32_e32 v5, v0
	v_mov_b32_e32 v6, v0
	v_mov_b32_e32 v7, v0
	v_mov_b32_e32 v16, v0
	v_mov_b32_e32 v17, v0
	v_mov_b32_e32 v18, v0
	v_mov_b32_e32 v19, v0
	v_mov_b32_e32 v20, v0
	v_mov_b32_e32 v21, v0
	v_mov_b32_e32 v22, v0
	v_mov_b32_e32 v23, v0
	v_mov_b32_e32 v32, v0
	v_mov_b32_e32 v33, v0
	v_mov_b32_e32 v34, v0
	v_mov_b32_e32 v35, v0
	v_mov_b32_e32 v36, v0
	v_mov_b32_e32 v37, v0
	v_mov_b32_e32 v38, v0
	v_mov_b32_e32 v39, v0
	v_mov_b32_e32 v48, v0
	v_mov_b32_e32 v49, v0
	v_mov_b32_e32 v50, v0
	v_mov_b32_e32 v51, v0
	v_mov_b32_e32 v52, v0
	v_mov_b32_e32 v53, v0
	v_mov_b32_e32 v54, v0
	v_mov_b32_e32 v55, v0
	v_mov_b32_e32 v8, v0
	v_mov_b32_e32 v9, v0
	v_mov_b32_e32 v10, v0
	v_mov_b32_e32 v11, v0
	v_mov_b32_e32 v12, v0
	v_mov_b32_e32 v13, v0
	v_mov_b32_e32 v14, v0
	v_mov_b32_e32 v15, v0
	v_mov_b32_e32 v24, v0
	v_mov_b32_e32 v25, v0
	v_mov_b32_e32 v26, v0
	v_mov_b32_e32 v27, v0
	v_mov_b32_e32 v28, v0
	v_mov_b32_e32 v29, v0
	v_mov_b32_e32 v30, v0
	v_mov_b32_e32 v31, v0
	v_mov_b32_e32 v40, v0
	v_mov_b32_e32 v41, v0
	v_mov_b32_e32 v42, v0
	v_mov_b32_e32 v43, v0
	v_mov_b32_e32 v44, v0
	v_mov_b32_e32 v45, v0
	v_mov_b32_e32 v46, v0
	v_mov_b32_e32 v47, v0
	v_mov_b32_e32 v56, v0
	v_mov_b32_e32 v57, v0
	v_mov_b32_e32 v58, v0
	v_mov_b32_e32 v59, v0
	v_mov_b32_e32 v60, v0
	v_mov_b32_e32 v61, v0
	v_mov_b32_e32 v62, v0
	v_mov_b32_e32 v63, v0
	v_mov_b32_e32 v64, v0
	v_mov_b32_e32 v65, v0
	v_mov_b32_e32 v66, v0
	v_mov_b32_e32 v67, v0
	v_mov_b32_e32 v68, v0
	v_mov_b32_e32 v69, v0
	v_mov_b32_e32 v70, v0
	v_mov_b32_e32 v71, v0
	v_mov_b32_e32 v80, v0
	v_mov_b32_e32 v81, v0
	v_mov_b32_e32 v82, v0
	v_mov_b32_e32 v83, v0
	v_mov_b32_e32 v84, v0
	v_mov_b32_e32 v85, v0
	v_mov_b32_e32 v86, v0
	v_mov_b32_e32 v87, v0
	v_mov_b32_e32 v102, v0
	v_mov_b32_e32 v103, v0
	v_mov_b32_e32 v104, v0
	v_mov_b32_e32 v105, v0
	v_mov_b32_e32 v106, v0
	v_mov_b32_e32 v107, v0
	v_mov_b32_e32 v108, v0
	v_mov_b32_e32 v109, v0
	v_mov_b32_e32 v118, v0
	v_mov_b32_e32 v119, v0
	v_mov_b32_e32 v120, v0
	v_mov_b32_e32 v121, v0
	v_mov_b32_e32 v122, v0
	v_mov_b32_e32 v123, v0
	v_mov_b32_e32 v124, v0
	v_mov_b32_e32 v125, v0
	v_mov_b32_e32 v72, v0
	v_mov_b32_e32 v73, v0
	v_mov_b32_e32 v74, v0
	v_mov_b32_e32 v75, v0
	v_mov_b32_e32 v76, v0
	v_mov_b32_e32 v77, v0
	v_mov_b32_e32 v78, v0
	v_mov_b32_e32 v79, v0
	v_mov_b32_e32 v88, v0
	v_mov_b32_e32 v89, v0
	v_mov_b32_e32 v90, v0
	v_mov_b32_e32 v91, v0
	v_mov_b32_e32 v92, v0
	v_mov_b32_e32 v93, v0
	v_mov_b32_e32 v94, v0
	v_mov_b32_e32 v95, v0
	v_mov_b32_e32 v110, v0
	v_mov_b32_e32 v111, v0
	v_mov_b32_e32 v112, v0
	v_mov_b32_e32 v113, v0
	v_mov_b32_e32 v114, v0
	v_mov_b32_e32 v115, v0
	v_mov_b32_e32 v116, v0
	v_mov_b32_e32 v117, v0
	v_mov_b32_e32 v134, v0
	v_mov_b32_e32 v135, v0
	v_mov_b32_e32 v136, v0
	v_mov_b32_e32 v137, v0
	v_mov_b32_e32 v138, v0
	v_mov_b32_e32 v139, v0
	v_mov_b32_e32 v140, v0
	v_mov_b32_e32 v141, v0
	s_cmp_gt_u32 s81, 0xff
	s_cbranch_scc0 .Lsp_1199
	s_setprio 1
.Lsp_1199:
.LBB0_1199:
	s_add_u32 s56, s54, 0xfff80080
	s_addc_u32 s57, s55, -1
	s_add_i32 s77, 0, 0x10000
	s_cmp_eq_u32 s76, 28
	s_cselect_b32 s59, s49, s57
	s_cselect_b32 s58, s71, s56
	s_cselect_b32 s57, s47, s75
	s_cselect_b32 s56, s72, s73
	s_add_i32 s80, 0, 0x14000
	v_add_u32_e32 v146, s77, v233
	v_add_u32_e32 v162, s80, v233
	ds_read_b128 v[126:129], v146
	ds_read_b128 v[130:133], v146 offset:1024
	ds_read_b128 v[142:145], v146 offset:2048
	ds_read_b128 v[146:149], v146 offset:3072
	ds_read_b128 v[150:153], v162
	ds_read_b128 v[154:157], v162 offset:1024
	ds_read_b128 v[158:161], v162 offset:2048
	ds_read_b128 v[162:165], v162 offset:3072
	v_lshl_add_u64 v[210:211], s[54:55], 0, v[192:193]
	s_add_i32 m0, s62, 0xc000
	ds_read_b128 v[166:169], v236
	ds_read_b128 v[170:173], v236 offset:1024
	ds_read_b128 v[174:177], v236 offset:2048
	ds_read_b128 v[178:181], v236 offset:3072
	ds_read_b128 v[194:197], v236 offset:4096
	ds_read_b128 v[198:201], v236 offset:5120
	ds_read_b128 v[202:205], v236 offset:6144
	ds_read_b128 v[206:209], v236 offset:7168
	global_load_lds_dwordx4 v[210:211], off
	v_lshl_add_u64 v[210:211], s[54:55], 0, v[190:191]
	s_add_i32 m0, s62, 0xe000
	s_nop 0
	global_load_lds_dwordx4 v[210:211], off
	s_waitcnt vmcnt(8)
	s_waitcnt lgkmcnt(0)
	s_barrier
; #define PG8_STAGE(bufoff, gbase, voff) do { _Pragma("unroll") for (int _i = 0; _i < 2; ++_i) \
;         __builtin_amdgcn_global_load_lds((const unsigned*)((const char*)(gbase) + (voff)[_i]), (PG8_LAS unsigned*)(lds + (bufoff) + ldsw + _i * 8192), 16, 0, 0); } while (0)
; #define PG8_LDA(dst, b, h) do { _Pragma("unroll") for (int m = 0; m < 4; ++m) _Pragma("unroll") for (int k = 0; k < 2; ++k) dst[m][k] = *(const PG8_LAS bf16x8*)(lds + PG8_SA(b, h) + aoff + m * 2048 + k * 1024); } while (0)
; #define PG8_MMA(ai, bj, At, Bt) do { __builtin_amdgcn_s_setprio(1); _Pragma("unroll") for (int m = 0; m < 4; ++m) _Pragma("unroll") for (int n = 0; n < 2; ++n) _Pragma("unroll") for (int k = 0; k < 2; ++k) \
;         acc[ai][bj][m][n] = __builtin_amdgcn_mfma_f32_16x16x32_bf16(Bt[n][k], At[m][k], acc[ai][bj][m][n], 0, 0, 0); __builtin_amdgcn_s_setprio(0); } while (0)
; #define PG8_WAIT_V(n) asm volatile("s_waitcnt vmcnt(" #n ")" ::: "memory")
; #define PG8_WAIT_L(n) asm volatile("s_waitcnt lgkmcnt(" #n ")" ::: "memory")
; #define PG8_BAR __builtin_amdgcn_s_barrier()
; #define PG8_SCHED __builtin_amdgcn_sched_barrier(0)
; template <class Epi, class Sched, bool ALIGN_EPI = false, bool SP2 = false>
; __device__ __forceinline__ void gemm_phase(PG8_LAS unsigned char* lds, const Gemm g, const Sched& S, const Epi& E, const int tid) {
;     ...
;             PG8_WAIT_V(8); PG8_WAIT_L(0); PG8_BAR; PG8_MMA(0, 0, At, B0); PG8_MMA(0, 1, At, B1); PG8_BAR; PG8_SCHED;
;             PG8_LDA(At, 0, 1); PG8_STAGE(PG8_SB(0, 0), b2, voffB); PG8_STAGE(PG8_SB(0, 1), b2 + hstep, voffB); PG8_STAGE(PG8_SA(0, 0), a2, voffA);
;             PG8_WAIT_V(8); PG8_WAIT_L(0); PG8_BAR; PG8_MMA(1, 0, At, B0); PG8_MMA(1, 1, At, B1); PG8_BAR; PG8_SCHED;
	v_mfma_f32_16x16x32_bf16 v[138:141], v[126:129], v[166:169], v[138:141]
	v_mfma_f32_16x16x32_bf16 v[134:137], v[142:145], v[166:169], v[134:137]
	v_mfma_f32_16x16x32_bf16 v[114:117], v[126:129], v[174:177], v[114:117]
	v_mfma_f32_16x16x32_bf16 v[110:113], v[142:145], v[174:177], v[110:113]
	v_mfma_f32_16x16x32_bf16 v[92:95], v[126:129], v[194:197], v[92:95]
	v_mfma_f32_16x16x32_bf16 v[88:91], v[142:145], v[194:197], v[88:91]
	v_mfma_f32_16x16x32_bf16 v[76:79], v[126:129], v[202:205], v[76:79]
	v_mfma_f32_16x16x32_bf16 v[72:75], v[142:145], v[202:205], v[72:75]
	v_mfma_f32_16x16x32_bf16 v[138:141], v[130:133], v[170:173], v[138:141]
	v_mfma_f32_16x16x32_bf16 v[134:137], v[146:149], v[170:173], v[134:137]
	v_mfma_f32_16x16x32_bf16 v[114:117], v[130:133], v[178:181], v[114:117]
	v_mfma_f32_16x16x32_bf16 v[110:113], v[146:149], v[178:181], v[110:113]
	v_mfma_f32_16x16x32_bf16 v[92:95], v[130:133], v[198:201], v[92:95]
	v_mfma_f32_16x16x32_bf16 v[88:91], v[146:149], v[198:201], v[88:91]
	v_mfma_f32_16x16x32_bf16 v[76:79], v[130:133], v[206:209], v[76:79]
	v_mfma_f32_16x16x32_bf16 v[72:75], v[146:149], v[206:209], v[72:75]
	v_mfma_f32_16x16x32_bf16 v[122:125], v[150:153], v[166:169], v[122:125]
	v_mfma_f32_16x16x32_bf16 v[118:121], v[158:161], v[166:169], v[118:121]
	v_mfma_f32_16x16x32_bf16 v[106:109], v[150:153], v[174:177], v[106:109]
	v_mfma_f32_16x16x32_bf16 v[102:105], v[158:161], v[174:177], v[102:105]
	v_mfma_f32_16x16x32_bf16 v[84:87], v[150:153], v[194:197], v[84:87]
	v_mfma_f32_16x16x32_bf16 v[80:83], v[158:161], v[194:197], v[80:83]
	v_mfma_f32_16x16x32_bf16 v[68:71], v[150:153], v[202:205], v[68:71]
	v_mfma_f32_16x16x32_bf16 v[64:67], v[158:161], v[202:205], v[64:67]
	v_mfma_f32_16x16x32_bf16 v[122:125], v[154:157], v[170:173], v[122:125]
	v_mfma_f32_16x16x32_bf16 v[118:121], v[162:165], v[170:173], v[118:121]
	v_mfma_f32_16x16x32_bf16 v[106:109], v[154:157], v[178:181], v[106:109]
	v_mfma_f32_16x16x32_bf16 v[102:105], v[162:165], v[178:181], v[102:105]
	v_mfma_f32_16x16x32_bf16 v[84:87], v[154:157], v[198:201], v[84:87]
	v_mfma_f32_16x16x32_bf16 v[80:83], v[162:165], v[198:201], v[80:83]
	v_mfma_f32_16x16x32_bf16 v[68:71], v[154:157], v[206:209], v[68:71]
	v_mfma_f32_16x16x32_bf16 v[64:67], v[162:165], v[206:209], v[64:67]
	s_barrier
	s_add_i32 s77, s77, s61
	v_lshl_add_u64 v[210:211], s[56:57], 0, v[96:97]
	s_mov_b32 m0, s77
	ds_read_b128 v[166:169], v236 offset:16384
	ds_read_b128 v[170:173], v236 offset:17408
	ds_read_b128 v[174:177], v236 offset:18432
	ds_read_b128 v[178:181], v236 offset:19456
	ds_read_b128 v[194:197], v236 offset:20480
	ds_read_b128 v[198:201], v236 offset:21504
	ds_read_b128 v[202:205], v236 offset:22528
	ds_read_b128 v[206:209], v236 offset:23552
	global_load_lds_dwordx4 v[210:211], off
	s_add_i32 m0, s77, 0x2000
	s_add_u32 s78, s56, 0x80000
	v_lshl_add_u64 v[212:213], s[56:57], 0, v[98:99]
	s_addc_u32 s79, s57, 0
	s_add_i32 s77, s80, s61
	global_load_lds_dwordx4 v[212:213], off
	v_lshl_add_u64 v[214:215], s[78:79], 0, v[96:97]
	s_mov_b32 m0, s77
	v_lshl_add_u64 v[216:217], s[58:59], 0, v[186:187]
	global_load_lds_dwordx4 v[214:215], off
	v_lshl_add_u64 v[214:215], s[78:79], 0, v[98:99]
	s_add_i32 m0, s77, 0x2000
	s_nop 0
	global_load_lds_dwordx4 v[214:215], off
	v_lshl_add_u64 v[214:215], s[58:59], 0, v[188:189]
	s_mov_b32 m0, s62
	s_nop 0
	global_load_lds_dwordx4 v[214:215], off
	s_mov_b32 m0, s63
	s_nop 0
	global_load_lds_dwordx4 v[216:217], off
	s_waitcnt vmcnt(8)
	s_waitcnt lgkmcnt(0)
	s_barrier
	v_mfma_f32_16x16x32_bf16 v[60:63], v[126:129], v[166:169], v[60:63]
	v_mfma_f32_16x16x32_bf16 v[56:59], v[142:145], v[166:169], v[56:59]
	v_mfma_f32_16x16x32_bf16 v[44:47], v[126:129], v[174:177], v[44:47]
	v_mfma_f32_16x16x32_bf16 v[40:43], v[142:145], v[174:177], v[40:43]
	v_mfma_f32_16x16x32_bf16 v[28:31], v[126:129], v[194:197], v[28:31]
	v_mfma_f32_16x16x32_bf16 v[24:27], v[142:145], v[194:197], v[24:27]
	v_mfma_f32_16x16x32_bf16 v[12:15], v[126:129], v[202:205], v[12:15]
	v_mfma_f32_16x16x32_bf16 v[8:11], v[142:145], v[202:205], v[8:11]
	v_mfma_f32_16x16x32_bf16 v[60:63], v[130:133], v[170:173], v[60:63]
	v_mfma_f32_16x16x32_bf16 v[56:59], v[146:149], v[170:173], v[56:59]
	v_mfma_f32_16x16x32_bf16 v[44:47], v[130:133], v[178:181], v[44:47]
	v_mfma_f32_16x16x32_bf16 v[40:43], v[146:149], v[178:181], v[40:43]
	v_mfma_f32_16x16x32_bf16 v[28:31], v[130:133], v[198:201], v[28:31]
	v_mfma_f32_16x16x32_bf16 v[24:27], v[146:149], v[198:201], v[24:27]
	v_mfma_f32_16x16x32_bf16 v[12:15], v[130:133], v[206:209], v[12:15]
	v_mfma_f32_16x16x32_bf16 v[8:11], v[146:149], v[206:209], v[8:11]
	v_mfma_f32_16x16x32_bf16 v[52:55], v[150:153], v[166:169], v[52:55]
	v_mfma_f32_16x16x32_bf16 v[48:51], v[158:161], v[166:169], v[48:51]
	v_mfma_f32_16x16x32_bf16 v[36:39], v[150:153], v[174:177], v[36:39]
	v_mfma_f32_16x16x32_bf16 v[32:35], v[158:161], v[174:177], v[32:35]
	v_mfma_f32_16x16x32_bf16 v[20:23], v[150:153], v[194:197], v[20:23]
	v_mfma_f32_16x16x32_bf16 v[16:19], v[158:161], v[194:197], v[16:19]
	v_mfma_f32_16x16x32_bf16 v[4:7], v[150:153], v[202:205], v[4:7]
	v_mfma_f32_16x16x32_bf16 v[0:3], v[158:161], v[202:205], v[0:3]
	v_mfma_f32_16x16x32_bf16 v[52:55], v[154:157], v[170:173], v[52:55]
	v_mfma_f32_16x16x32_bf16 v[48:51], v[162:165], v[170:173], v[48:51]
	v_mfma_f32_16x16x32_bf16 v[36:39], v[154:157], v[178:181], v[36:39]
	v_mfma_f32_16x16x32_bf16 v[32:35], v[162:165], v[178:181], v[32:35]
	v_mfma_f32_16x16x32_bf16 v[20:23], v[154:157], v[198:201], v[20:23]
	v_mfma_f32_16x16x32_bf16 v[16:19], v[162:165], v[198:201], v[16:19]
	v_mfma_f32_16x16x32_bf16 v[4:7], v[154:157], v[206:209], v[4:7]
	v_mfma_f32_16x16x32_bf16 v[0:3], v[162:165], v[206:209], v[0:3]
	s_barrier
; #define PG8_STAGE(bufoff, gbase, voff) do { _Pragma("unroll") for (int _i = 0; _i < 2; ++_i) \
;         __builtin_amdgcn_global_load_lds((const unsigned*)((const char*)(gbase) + (voff)[_i]), (PG8_LAS unsigned*)(lds + (bufoff) + ldsw + _i * 8192), 16, 0, 0); } while (0)
; #define PG8_LDA(dst, b, h) do { _Pragma("unroll") for (int m = 0; m < 4; ++m) _Pragma("unroll") for (int k = 0; k < 2; ++k) dst[m][k] = *(const PG8_LAS bf16x8*)(lds + PG8_SA(b, h) + aoff + m * 2048 + k * 1024); } while (0)
; #define PG8_LDB(dst, b, h) do { _Pragma("unroll") for (int n = 0; n < 2; ++n) _Pragma("unroll") for (int k = 0; k < 2; ++k) dst[n][k] = *(const PG8_LAS bf16x8*)(lds + PG8_SB(b, h) + boff + n * 2048 + k * 1024); } while (0)
; #define PG8_MMA(ai, bj, At, Bt) do { __builtin_amdgcn_s_setprio(1); _Pragma("unroll") for (int m = 0; m < 4; ++m) _Pragma("unroll") for (int n = 0; n < 2; ++n) _Pragma("unroll") for (int k = 0; k < 2; ++k) \
;         acc[ai][bj][m][n] = __builtin_amdgcn_mfma_f32_16x16x32_bf16(Bt[n][k], At[m][k], acc[ai][bj][m][n], 0, 0, 0); __builtin_amdgcn_s_setprio(0); } while (0)
; #define PG8_WAIT_V(n) asm volatile("s_waitcnt vmcnt(" #n ")" ::: "memory")
; #define PG8_WAIT_L(n) asm volatile("s_waitcnt lgkmcnt(" #n ")" ::: "memory")
; #define PG8_BAR __builtin_amdgcn_s_barrier()
; #define PG8_SCHED __builtin_amdgcn_sched_barrier(0)
; template <class Epi, class Sched, bool ALIGN_EPI = false, bool SP2 = false>
; __device__ __forceinline__ void gemm_phase(PG8_LAS unsigned char* lds, const Gemm g, const Sched& S, const Epi& E, const int tid) {
;     ...
;             PG8_LDB(B0, 1, 0); PG8_LDB(B1, 1, 1); PG8_SCHED; PG8_LDA(At, 1, 0); PG8_STAGE(PG8_SA(0, 1), a2 + hstep, voffA);
;             PG8_WAIT_V(8); PG8_WAIT_L(0); PG8_BAR; PG8_MMA(0, 0, At, B0); PG8_MMA(0, 1, At, B1); PG8_BAR; PG8_SCHED;
;             PG8_LDA(At, 1, 1); PG8_STAGE(PG8_SB(1, 0), b3, voffB); PG8_STAGE(PG8_SB(1, 1), b3 + hstep, voffB); PG8_STAGE(PG8_SA(1, 0), a3, voffA);
	s_add_i32 s77, 0, 0x18000
	s_add_i32 s78, 0, 0x1c000
	v_add_u32_e32 v146, s77, v233
	v_add_u32_e32 v162, s78, v233
	ds_read_b128 v[126:129], v146
	ds_read_b128 v[130:133], v146 offset:1024
	ds_read_b128 v[142:145], v146 offset:2048
	ds_read_b128 v[146:149], v146 offset:3072
	ds_read_b128 v[150:153], v162
	ds_read_b128 v[154:157], v162 offset:1024
	ds_read_b128 v[158:161], v162 offset:2048
	ds_read_b128 v[162:165], v162 offset:3072
	s_add_u32 s58, s58, 0x80000
	s_addc_u32 s59, s59, 0
	s_mov_b32 m0, s64
	v_lshl_add_u64 v[218:219], s[58:59], 0, v[188:189]
	ds_read_b128 v[166:169], v236 offset:32768
	ds_read_b128 v[170:173], v236 offset:33792
	ds_read_b128 v[174:177], v236 offset:34816
	ds_read_b128 v[178:181], v236 offset:35840
	ds_read_b128 v[194:197], v236 offset:36864
	ds_read_b128 v[198:201], v236 offset:37888
	ds_read_b128 v[202:205], v236 offset:38912
	ds_read_b128 v[206:209], v236 offset:39936
	global_load_lds_dwordx4 v[218:219], off
	v_lshl_add_u64 v[218:219], s[58:59], 0, v[186:187]
	s_mov_b32 m0, s65
	s_nop 0
	global_load_lds_dwordx4 v[218:219], off
	s_waitcnt vmcnt(8)
	s_waitcnt lgkmcnt(0)
	s_barrier
	v_mfma_f32_16x16x32_bf16 v[138:141], v[126:129], v[166:169], v[138:141]
	v_mfma_f32_16x16x32_bf16 v[134:137], v[142:145], v[166:169], v[134:137]
	v_mfma_f32_16x16x32_bf16 v[114:117], v[126:129], v[174:177], v[114:117]
	v_mfma_f32_16x16x32_bf16 v[110:113], v[142:145], v[174:177], v[110:113]
	v_mfma_f32_16x16x32_bf16 v[92:95], v[126:129], v[194:197], v[92:95]
	v_mfma_f32_16x16x32_bf16 v[88:91], v[142:145], v[194:197], v[88:91]
	v_mfma_f32_16x16x32_bf16 v[76:79], v[126:129], v[202:205], v[76:79]
	v_mfma_f32_16x16x32_bf16 v[72:75], v[142:145], v[202:205], v[72:75]
	v_mfma_f32_16x16x32_bf16 v[138:141], v[130:133], v[170:173], v[138:141]
	v_mfma_f32_16x16x32_bf16 v[134:137], v[146:149], v[170:173], v[134:137]
	v_mfma_f32_16x16x32_bf16 v[114:117], v[130:133], v[178:181], v[114:117]
	v_mfma_f32_16x16x32_bf16 v[110:113], v[146:149], v[178:181], v[110:113]
	v_mfma_f32_16x16x32_bf16 v[92:95], v[130:133], v[198:201], v[92:95]
	v_mfma_f32_16x16x32_bf16 v[88:91], v[146:149], v[198:201], v[88:91]
	v_mfma_f32_16x16x32_bf16 v[76:79], v[130:133], v[206:209], v[76:79]
	v_mfma_f32_16x16x32_bf16 v[72:75], v[146:149], v[206:209], v[72:75]
	v_mfma_f32_16x16x32_bf16 v[122:125], v[150:153], v[166:169], v[122:125]
	v_mfma_f32_16x16x32_bf16 v[118:121], v[158:161], v[166:169], v[118:121]
	v_mfma_f32_16x16x32_bf16 v[106:109], v[150:153], v[174:177], v[106:109]
	v_mfma_f32_16x16x32_bf16 v[102:105], v[158:161], v[174:177], v[102:105]
	v_mfma_f32_16x16x32_bf16 v[84:87], v[150:153], v[194:197], v[84:87]
	v_mfma_f32_16x16x32_bf16 v[80:83], v[158:161], v[194:197], v[80:83]
	v_mfma_f32_16x16x32_bf16 v[68:71], v[150:153], v[202:205], v[68:71]
	v_mfma_f32_16x16x32_bf16 v[64:67], v[158:161], v[202:205], v[64:67]
	v_mfma_f32_16x16x32_bf16 v[122:125], v[154:157], v[170:173], v[122:125]
	v_mfma_f32_16x16x32_bf16 v[118:121], v[162:165], v[170:173], v[118:121]
	v_mfma_f32_16x16x32_bf16 v[106:109], v[154:157], v[178:181], v[106:109]
	v_mfma_f32_16x16x32_bf16 v[102:105], v[162:165], v[178:181], v[102:105]
	v_mfma_f32_16x16x32_bf16 v[84:87], v[154:157], v[198:201], v[84:87]
	v_mfma_f32_16x16x32_bf16 v[80:83], v[162:165], v[198:201], v[80:83]
	v_mfma_f32_16x16x32_bf16 v[68:71], v[154:157], v[206:209], v[68:71]
	v_mfma_f32_16x16x32_bf16 v[64:67], v[162:165], v[206:209], v[64:67]
	s_barrier
	s_add_i32 s58, s77, s61
	v_lshl_add_u64 v[210:211], v[210:211], 0, s[28:29]
	s_mov_b32 m0, s58
	ds_read_b128 v[166:169], v236 offset:49152
	ds_read_b128 v[170:173], v236 offset:50176
	ds_read_b128 v[174:177], v236 offset:51200
	ds_read_b128 v[178:181], v236 offset:52224
	ds_read_b128 v[194:197], v236 offset:53248
	ds_read_b128 v[198:201], v236 offset:54272
	ds_read_b128 v[202:205], v236 offset:55296
	ds_read_b128 v[206:209], v236 offset:56320
	global_load_lds_dwordx4 v[210:211], off
	s_add_i32 m0, s58, 0x2000
	s_add_u32 s56, s56, 0x80080
	v_lshl_add_u64 v[210:211], v[212:213], 0, s[28:29]
	s_addc_u32 s57, s57, 0
	s_add_i32 s58, s78, s61
	global_load_lds_dwordx4 v[210:211], off
	v_lshl_add_u64 v[210:211], s[56:57], 0, v[96:97]
	s_mov_b32 m0, s58
	s_nop 0
	global_load_lds_dwordx4 v[210:211], off
	v_lshl_add_u64 v[210:211], s[56:57], 0, v[98:99]
	s_add_i32 m0, s58, 0x2000
	s_nop 0
	global_load_lds_dwordx4 v[210:211], off
	v_lshl_add_u64 v[210:211], v[214:215], 0, s[28:29]
	s_mov_b32 m0, s66
	s_nop 0
	global_load_lds_dwordx4 v[210:211], off
	v_lshl_add_u64 v[210:211], v[216:217], 0, s[28:29]
	s_mov_b32 m0, s67
	s_nop 0
	global_load_lds_dwordx4 v[210:211], off
	s_waitcnt vmcnt(8)
	s_waitcnt lgkmcnt(0)
	s_barrier
; #define PG8_GAS __attribute__((address_space(1)))
; #define PG8_MMA(ai, bj, At, Bt) do { __builtin_amdgcn_s_setprio(1); _Pragma("unroll") for (int m = 0; m < 4; ++m) _Pragma("unroll") for (int n = 0; n < 2; ++n) _Pragma("unroll") for (int k = 0; k < 2; ++k) \
;         acc[ai][bj][m][n] = __builtin_amdgcn_mfma_f32_16x16x32_bf16(Bt[n][k], At[m][k], acc[ai][bj][m][n], 0, 0, 0); __builtin_amdgcn_s_setprio(0); } while (0)
; #define PG8_WAIT_V(n) asm volatile("s_waitcnt vmcnt(" #n ")" ::: "memory")
; #define PG8_WAIT_L(n) asm volatile("s_waitcnt lgkmcnt(" #n ")" ::: "memory")
; #define PG8_BAR __builtin_amdgcn_s_barrier()
; #define PG8_SCHED __builtin_amdgcn_sched_barrier(0)
;     __device__ __forceinline__ void operator()(const f32x4 (&acc)[2][2][4][2], const Unit& u, int wr, int wc, int fr, int fq) const {
;         const int row0 = u.pm * BM + wr * 64 + fr, col0 = u.pn * BM + wc * 32 + 8 * fq, lcol = u.pn * BM + (wc * 4 + fq) * 16;
; #pragma unroll
;         for (int ai = 0; ai < 2; ++ai) {
;             u32x4 L4[4], H4[4][2];
; #pragma unroll
;             for (int m = 0; m < 4; ++m) {
;                 const int row = row0 + ai * HALF + m * 16; const size_t off = (size_t)row * 2048 + col0, loff = (size_t)row * 2048 + lcol;
;                 L4[m] = *(const PG8_GAS u32x4*)(lin + loff); H4[m][0] = *(const PG8_GAS u32x4*)(hin + off); H4[m][1] = *(const PG8_GAS u32x4*)(hin + off + HALF);
;             }
; template <class Epi, class Sched, bool ALIGN_EPI = false, bool SP2 = false>
; __device__ __forceinline__ void gemm_phase(PG8_LAS unsigned char* lds, const Gemm g, const Sched& S, const Epi& E, const int tid) {
;     ...
;             PG8_WAIT_V(8); PG8_WAIT_L(0); PG8_BAR; PG8_MMA(1, 0, At, B0); PG8_MMA(1, 1, At, B1); PG8_BAR; PG8_SCHED;
	v_mfma_f32_16x16x32_bf16 v[60:63], v[126:129], v[166:169], v[60:63]
	v_mfma_f32_16x16x32_bf16 v[56:59], v[142:145], v[166:169], v[56:59]
	v_mfma_f32_16x16x32_bf16 v[44:47], v[126:129], v[174:177], v[44:47]
	v_mfma_f32_16x16x32_bf16 v[40:43], v[142:145], v[174:177], v[40:43]
	v_mfma_f32_16x16x32_bf16 v[28:31], v[126:129], v[194:197], v[28:31]
	v_mfma_f32_16x16x32_bf16 v[24:27], v[142:145], v[194:197], v[24:27]
	v_mfma_f32_16x16x32_bf16 v[12:15], v[126:129], v[202:205], v[12:15]
	v_mfma_f32_16x16x32_bf16 v[8:11], v[142:145], v[202:205], v[8:11]
	v_mfma_f32_16x16x32_bf16 v[60:63], v[130:133], v[170:173], v[60:63]
	v_mfma_f32_16x16x32_bf16 v[56:59], v[146:149], v[170:173], v[56:59]
	v_mfma_f32_16x16x32_bf16 v[44:47], v[130:133], v[178:181], v[44:47]
	v_mfma_f32_16x16x32_bf16 v[40:43], v[146:149], v[178:181], v[40:43]
	v_mfma_f32_16x16x32_bf16 v[28:31], v[130:133], v[198:201], v[28:31]
	v_mfma_f32_16x16x32_bf16 v[24:27], v[146:149], v[198:201], v[24:27]
	v_mfma_f32_16x16x32_bf16 v[12:15], v[130:133], v[206:209], v[12:15]
	v_mfma_f32_16x16x32_bf16 v[8:11], v[146:149], v[206:209], v[8:11]
	v_mfma_f32_16x16x32_bf16 v[52:55], v[150:153], v[166:169], v[52:55]
	v_mfma_f32_16x16x32_bf16 v[48:51], v[158:161], v[166:169], v[48:51]
	v_mfma_f32_16x16x32_bf16 v[36:39], v[150:153], v[174:177], v[36:39]
	v_mfma_f32_16x16x32_bf16 v[32:35], v[158:161], v[174:177], v[32:35]
	v_mfma_f32_16x16x32_bf16 v[20:23], v[150:153], v[194:197], v[20:23]
	v_mfma_f32_16x16x32_bf16 v[16:19], v[158:161], v[194:197], v[16:19]
	v_mfma_f32_16x16x32_bf16 v[4:7], v[150:153], v[202:205], v[4:7]
	v_mfma_f32_16x16x32_bf16 v[0:3], v[158:161], v[202:205], v[0:3]
	v_mfma_f32_16x16x32_bf16 v[52:55], v[154:157], v[170:173], v[52:55]
	v_mfma_f32_16x16x32_bf16 v[48:51], v[162:165], v[170:173], v[48:51]
	v_mfma_f32_16x16x32_bf16 v[36:39], v[154:157], v[178:181], v[36:39]
	v_mfma_f32_16x16x32_bf16 v[32:35], v[162:165], v[178:181], v[32:35]
	v_mfma_f32_16x16x32_bf16 v[20:23], v[154:157], v[198:201], v[20:23]
	v_mfma_f32_16x16x32_bf16 v[16:19], v[162:165], v[198:201], v[16:19]
	v_mfma_f32_16x16x32_bf16 v[4:7], v[154:157], v[206:209], v[4:7]
	v_mfma_f32_16x16x32_bf16 v[0:3], v[162:165], v[206:209], v[0:3]
	s_barrier
	s_add_i32 s76, s76, 2
	s_add_u32 s73, s73, 0x100
	s_addc_u32 s75, s75, 0
	s_add_u32 s54, s54, 0x100
	s_addc_u32 s55, s55, 0
	s_cmp_gt_u32 s76, 29
	s_cbranch_scc0 .LBB0_1199
	s_setprio 0
	v_and_b32_e32 v127, 64, v228
	v_xor_b32_e32 v126, 16, v228
	v_add_u32_e32 v127, 64, v127
	v_cmp_lt_i32_e32 vcc, v126, v127
	s_lshl_b32 s47, s69, 8
	v_lshl_add_u32 v198, s70, 8, v101
	v_cndmask_b32_e32 v126, v228, v126, vcc
	v_or_b32_e32 v194, s47, v235
	v_lshlrev_b32_e32 v238, 2, v126
	v_xor_b32_e32 v126, 32, v228
	v_or_b32_e32 v196, s47, v234
	v_ashrrev_i32_e32 v195, 31, v194
	v_cmp_lt_i32_e32 vcc, v126, v127
	v_ashrrev_i32_e32 v199, 31, v198
	v_ashrrev_i32_e32 v197, 31, v196
	v_cndmask_b32_e32 v126, v228, v126, vcc
	v_lshl_add_u64 v[202:203], s[34:35], 0, v[194:195]
	v_lshlrev_b64 v[216:217], 11, v[198:199]
	v_lshlrev_b32_e32 v237, 2, v126
	v_lshlrev_b64 v[218:219], 1, v[196:197]
	v_lshl_add_u64 v[126:127], v[202:203], 0, v[216:217]
	v_lshl_add_u64 v[200:201], s[30:31], 0, v[218:219]
	global_load_dwordx4 v[170:173], v[126:127], off
	v_lshlrev_b64 v[220:221], 12, v[198:199]
	v_lshl_add_u64 v[126:127], v[200:201], 0, v[220:221]
	global_load_dwordx4 v[178:181], v[126:127], off
	global_load_dwordx4 v[174:177], v[126:127], off offset:256
	v_or_b32_e32 v212, 16, v198
	v_ashrrev_i32_e32 v213, 31, v212
	v_lshlrev_b64 v[214:215], 11, v[212:213]
	v_lshl_add_u64 v[126:127], v[202:203], 0, v[214:215]
	v_or_b32_e32 v208, 32, v198
	global_load_dwordx4 v[158:161], v[126:127], off
	v_lshlrev_b64 v[126:127], 12, v[212:213]
	v_ashrrev_i32_e32 v209, 31, v208
	v_lshl_add_u64 v[126:127], v[200:201], 0, v[126:127]
	v_lshlrev_b64 v[210:211], 11, v[208:209]
	global_load_dwordx4 v[166:169], v[126:127], off
	global_load_dwordx4 v[162:165], v[126:127], off offset:256
	v_lshl_add_u64 v[126:127], v[202:203], 0, v[210:211]
	v_or_b32_e32 v204, 48, v198
	global_load_dwordx4 v[146:149], v[126:127], off
	v_lshlrev_b64 v[126:127], 12, v[208:209]
	v_ashrrev_i32_e32 v205, 31, v204
	v_lshl_add_u64 v[126:127], v[200:201], 0, v[126:127]
	v_lshlrev_b64 v[206:207], 11, v[204:205]
	v_lshlrev_b64 v[130:131], 12, v[204:205]
	global_load_dwordx4 v[154:157], v[126:127], off
	global_load_dwordx4 v[150:153], v[126:127], off offset:256
	v_lshl_add_u64 v[126:127], v[202:203], 0, v[206:207]
	v_lshl_add_u64 v[130:131], v[200:201], 0, v[130:131]
	global_load_dwordx4 v[126:129], v[126:127], off
	s_nop 0
	global_load_dwordx4 v[142:145], v[130:131], off
	s_nop 0
	global_load_dwordx4 v[130:133], v[130:131], off offset:256
	v_mov_b32_e32 v225, v134
	v_mov_b32_e32 v243, v136
	v_mov_b32_e32 v242, v140
	s_waitcnt vmcnt(0)
; #define PG8_GAS __attribute__((address_space(1)))
; __device__ __forceinline__ float e_x24(unsigned h16, unsigned l8) { return __uint_as_float(((h16 - (l8 >> 7)) << 16) | (l8 << 8)); }
;     __device__ __forceinline__ void operator()(const f32x4 (&acc)[2][2][4][2], const Unit& u, int wr, int wc, int fr, int fq) const {
;     ...
;             for (int m = 0; m < 4; ++m) {
;                 const int row = row0 + ai * HALF + m * 16; const size_t off = (size_t)row * 2048 + col0, loff = (size_t)row * 2048 + lcol; float ss = 0.f;
;                 const u32x4 l4 = L4[m];
;                 u32x4 lo4;
; #pragma unroll
;                 for (int bj = 0; bj < 2; ++bj) {
;                     const u32x4 h4 = H4[m][bj];
;                     u32x4 ho;
; #pragma unroll
;                     for (int j = 0; j < 4; ++j) {
;                         const unsigned lw = l4[2 * bj + (j >> 1)], lb0 = (lw >> (16 * (j & 1))) & 0xffu, lb1 = (lw >> (16 * (j & 1) + 8)) & 0xffu;
;                         const float x0 = e_x24(h4[j] & 0xffffu, lb0) + acc[ai][bj][m][j >> 1][2 * (j & 1)] * scale, x1 = e_x24(h4[j] >> 16, lb1) + acc[ai][bj][m][j >> 1][2 * (j & 1) + 1] * scale;
;                         const unsigned b0 = __float_as_uint(x0), b1 = __float_as_uint(x1);
;                         ho[j] = ((b0 + 0x8000u) >> 16) | ((b1 + 0x8000u) & 0xffff0000u);
;                         const unsigned nb = ((b0 >> 8) & 0xffu) | (b1 & 0xff00u);
;                         if ((j & 1) == 0) lo4[2 * bj + (j >> 1)] = nb; else lo4[2 * bj + (j >> 1)] |= nb << 16;
;                         ss += x0 * x0 + x1 * x1;
;                     }
;                     *(PG8_GAS u32x4*)(hout + off + bj * HALF) = ho;
	v_lshrrev_b32_sdwa v182, v229, v171 dst_sel:DWORD dst_unused:UNUSED_PAD src0_sel:DWORD src1_sel:BYTE_0
	v_lshrrev_b32_sdwa v183, v229, v170 dst_sel:DWORD dst_unused:UNUSED_PAD src0_sel:DWORD src1_sel:BYTE_0
	v_sub_u32_sdwa v183, v178, v183 dst_sel:WORD_1 dst_unused:UNUSED_PAD src0_sel:DWORD src1_sel:DWORD
	v_sub_u32_sdwa v182, v180, v182 dst_sel:WORD_1 dst_unused:UNUSED_PAD src0_sel:DWORD src1_sel:DWORD
	v_lshlrev_b32_sdwa v222, v230, v171 dst_sel:DWORD dst_unused:UNUSED_PAD src0_sel:DWORD src1_sel:BYTE_0
	v_lshlrev_b32_sdwa v224, v230, v170 dst_sel:DWORD dst_unused:UNUSED_PAD src0_sel:DWORD src1_sel:BYTE_0
	v_or_b32_e32 v223, v182, v222
	v_or_b32_e32 v222, v183, v224
	v_mov_b32_e32 v224, v138
	v_pk_add_f32 v[222:223], v[224:225], v[222:223]
	v_lshlrev_b32_e32 v182, 1, v170
	v_add_u32_e32 v134, 0x8000, v222
	v_lshrrev_b32_e32 v138, 16, v134
	v_lshlrev_b32_e32 v134, 1, v171
	v_and_b32_e32 v134, 0x10000, v134
	v_and_b32_e32 v182, 0x10000, v182
	v_sub_u32_e32 v134, v180, v134
	v_sub_u32_e32 v178, v178, v182
	v_and_b32_e32 v134, 0xffff0000, v134
	v_and_b32_e32 v178, 0xffff0000, v178
	v_and_b32_e32 v180, 0xff00, v171
	v_and_b32_e32 v182, 0xff00, v170
	v_or_b32_e32 v225, v134, v180
	v_or_b32_e32 v224, v178, v182
	v_mov_b32_e32 v134, v139
	v_pk_add_f32 v[224:225], v[134:135], v[224:225]
	v_and_b32_sdwa v135, v171, s93 dst_sel:DWORD dst_unused:UNUSED_PAD src0_sel:WORD_1 src1_sel:DWORD
	v_and_b32_sdwa v178, v170, s93 dst_sel:DWORD dst_unused:UNUSED_PAD src0_sel:WORD_1 src1_sel:DWORD
	v_lshlrev_b32_sdwa v182, v231, v170 dst_sel:DWORD dst_unused:UNUSED_PAD src0_sel:DWORD src1_sel:BYTE_3
	v_lshlrev_b32_sdwa v136, v231, v171 dst_sel:DWORD dst_unused:UNUSED_PAD src0_sel:DWORD src1_sel:BYTE_3
	v_lshrrev_b32_e32 v180, 7, v178
	v_lshrrev_b32_e32 v183, 7, v135
	v_and_b32_e32 v136, 0x10000, v136
	v_and_b32_e32 v140, 0x10000, v182
	v_sub_u32_sdwa v180, v179, v180 dst_sel:WORD_1 dst_unused:UNUSED_PAD src0_sel:DWORD src1_sel:DWORD
	v_sub_u32_sdwa v183, v181, v183 dst_sel:WORD_1 dst_unused:UNUSED_PAD src0_sel:DWORD src1_sel:DWORD
	v_lshlrev_b32_e32 v135, 8, v135
	v_lshlrev_b32_e32 v178, 8, v178
	v_sub_u32_e32 v136, v181, v136
	v_sub_u32_e32 v140, v179, v140
	v_or_b32_e32 v241, v183, v135
	v_or_b32_e32 v240, v180, v178
	v_and_b32_e32 v136, 0xffff0000, v136
	v_and_b32_e32 v140, 0xffff0000, v140
	v_lshlrev_b32_sdwa v171, v230, v171 dst_sel:DWORD dst_unused:UNUSED_PAD src0_sel:DWORD src1_sel:BYTE_3
	v_lshlrev_b32_sdwa v170, v230, v170 dst_sel:DWORD dst_unused:UNUSED_PAD src0_sel:DWORD src1_sel:BYTE_3
	v_pk_add_f32 v[240:241], v[242:243], v[240:241]
	v_or_b32_e32 v171, v136, v171
	v_or_b32_e32 v170, v140, v170
	v_mov_b32_e32 v136, v141
	v_add_u32_e32 v135, 0x8000, v240
	v_pk_add_f32 v[140:141], v[136:137], v[170:171]
	v_lshrrev_b32_e32 v135, 16, v135
	v_add_u32_e32 v136, 0x8000, v140
	v_and_or_b32 v135, v136, s90, v135
	v_pk_mul_f32 v[136:137], v[140:141], v[140:141]
	v_add_u32_e32 v178, 0x8000, v141
	v_pk_fma_f32 v[170:171], v[240:241], v[240:241], v[136:137]
	v_add_u32_e32 v136, 0x8000, v223
	v_lshrrev_b32_e32 v136, 16, v136
	v_add_u32_e32 v137, 0x8000, v225
	v_and_or_b32 v136, v137, s90, v136
	v_add_u32_e32 v137, 0x8000, v241
	v_lshrrev_b32_e32 v137, 16, v137
	v_add_u32_e32 v134, 0x8000, v224
	v_and_or_b32 v137, v178, s90, v137
	v_lshl_add_u64 v[178:179], s[30:31], 0, v[220:221]
	v_and_or_b32 v134, v134, s90, v138
	v_lshl_add_u64 v[178:179], v[178:179], 0, v[218:219]
	global_store_dwordx4 v[178:179], v[134:137], off
	v_lshlrev_b32_sdwa v182, v231, v172 dst_sel:DWORD dst_unused:UNUSED_PAD src0_sel:DWORD src1_sel:BYTE_3
	v_mov_b32_e32 v219, v120
	v_lshrrev_b32_sdwa v134, v229, v173 dst_sel:DWORD dst_unused:UNUSED_PAD src0_sel:DWORD src1_sel:BYTE_0
	v_lshrrev_b32_sdwa v135, v229, v172 dst_sel:DWORD dst_unused:UNUSED_PAD src0_sel:DWORD src1_sel:BYTE_0
	v_sub_u32_sdwa v136, v174, v135 dst_sel:WORD_1 dst_unused:UNUSED_PAD src0_sel:DWORD src1_sel:DWORD
	v_sub_u32_sdwa v134, v176, v134 dst_sel:WORD_1 dst_unused:UNUSED_PAD src0_sel:DWORD src1_sel:DWORD
	v_lshlrev_b32_sdwa v135, v230, v173 dst_sel:DWORD dst_unused:UNUSED_PAD src0_sel:DWORD src1_sel:BYTE_0
	v_lshlrev_b32_sdwa v137, v230, v172 dst_sel:DWORD dst_unused:UNUSED_PAD src0_sel:DWORD src1_sel:BYTE_0
	v_or_b32_e32 v135, v134, v135
	v_or_b32_e32 v134, v136, v137
	v_mov_b32_e32 v136, v122
	v_mov_b32_e32 v137, v118
	v_pk_add_f32 v[134:135], v[136:137], v[134:135]
	v_lshlrev_b32_e32 v122, 1, v172
; #define PG8_GAS __attribute__((address_space(1)))
; __device__ __forceinline__ float e_x24(unsigned h16, unsigned l8) { return __uint_as_float(((h16 - (l8 >> 7)) << 16) | (l8 << 8)); }
;     __device__ __forceinline__ void operator()(const f32x4 (&acc)[2][2][4][2], const Unit& u, int wr, int wc, int fr, int fq) const {
;     ...
;             for (int m = 0; m < 4; ++m) {
;                 const int row = row0 + ai * HALF + m * 16; const size_t off = (size_t)row * 2048 + col0, loff = (size_t)row * 2048 + lcol; float ss = 0.f;
;                 const u32x4 l4 = L4[m];
;                 u32x4 lo4;
; #pragma unroll
;                 for (int bj = 0; bj < 2; ++bj) {
;                     const u32x4 h4 = H4[m][bj];
;                     u32x4 ho;
; #pragma unroll
;                     for (int j = 0; j < 4; ++j) {
;                         const unsigned lw = l4[2 * bj + (j >> 1)], lb0 = (lw >> (16 * (j & 1))) & 0xffu, lb1 = (lw >> (16 * (j & 1) + 8)) & 0xffu;
;                         const float x0 = e_x24(h4[j] & 0xffffu, lb0) + acc[ai][bj][m][j >> 1][2 * (j & 1)] * scale, x1 = e_x24(h4[j] >> 16, lb1) + acc[ai][bj][m][j >> 1][2 * (j & 1) + 1] * scale;
;                         const unsigned b0 = __float_as_uint(x0), b1 = __float_as_uint(x1);
;                         ho[j] = ((b0 + 0x8000u) >> 16) | ((b1 + 0x8000u) & 0xffff0000u);
;                         const unsigned nb = ((b0 >> 8) & 0xffu) | (b1 & 0xff00u);
;                         if ((j & 1) == 0) lo4[2 * bj + (j >> 1)] = nb; else lo4[2 * bj + (j >> 1)] |= nb << 16;
;                         ss += x0 * x0 + x1 * x1;
;                     }
;                     *(PG8_GAS u32x4*)(hout + off + bj * HALF) = ho;
;                 }
;                 *(PG8_GAS u32x4*)(lout + loff) = lo4;
;                 ss += __shfl_xor(ss, 16); ss += __shfl_xor(ss, 32);
;                 if (fq == 0) __hip_atomic_fetch_add((PG8_GAS unsigned long long*)(rowsq_out + row), (unsigned long long)(ss * 16777216.0f + 0.5f), __ATOMIC_RELAXED, __HIP_MEMORY_SCOPE_AGENT);
	v_add_u32_e32 v118, 0x8000, v134
	v_lshrrev_b32_e32 v180, 16, v118
	v_lshlrev_b32_e32 v118, 1, v173
	v_and_b32_e32 v118, 0x10000, v118
	v_and_b32_e32 v122, 0x10000, v122
	v_sub_u32_e32 v118, v176, v118
	v_sub_u32_e32 v122, v174, v122
	v_and_b32_e32 v118, 0xffff0000, v118
	v_and_b32_e32 v122, 0xffff0000, v122
	v_and_b32_e32 v136, 0xff00, v173
	v_and_b32_e32 v174, 0xff00, v172
	v_or_b32_e32 v137, v118, v136
	v_or_b32_e32 v136, v122, v174
	v_mov_b32_e32 v118, v123
	v_pk_add_f32 v[122:123], v[118:119], v[136:137]
	v_and_b32_sdwa v119, v173, s93 dst_sel:DWORD dst_unused:UNUSED_PAD src0_sel:WORD_1 src1_sel:DWORD
	v_add_u32_e32 v118, 0x8000, v122
	v_and_b32_sdwa v174, v172, s93 dst_sel:DWORD dst_unused:UNUSED_PAD src0_sel:WORD_1 src1_sel:DWORD
	v_lshlrev_b32_sdwa v120, v231, v173 dst_sel:DWORD dst_unused:UNUSED_PAD src0_sel:DWORD src1_sel:BYTE_3
	v_and_or_b32 v118, v118, s90, v180
	v_lshrrev_b32_e32 v176, 7, v174
	v_lshrrev_b32_e32 v180, 7, v119
	v_mov_b32_e32 v218, v124
	v_and_b32_e32 v120, 0x10000, v120
	v_and_b32_e32 v124, 0x10000, v182
	v_sub_u32_sdwa v176, v175, v176 dst_sel:WORD_1 dst_unused:UNUSED_PAD src0_sel:DWORD src1_sel:DWORD
	v_sub_u32_sdwa v180, v177, v180 dst_sel:WORD_1 dst_unused:UNUSED_PAD src0_sel:DWORD src1_sel:DWORD
	v_lshlrev_b32_e32 v119, 8, v119
	v_lshlrev_b32_e32 v174, 8, v174
	v_sub_u32_e32 v120, v177, v120
	v_sub_u32_e32 v124, v175, v124
	v_or_b32_e32 v181, v180, v119
	v_or_b32_e32 v180, v176, v174
	v_and_b32_e32 v120, 0xffff0000, v120
	v_and_b32_e32 v124, 0xffff0000, v124
	v_lshlrev_b32_sdwa v173, v230, v173 dst_sel:DWORD dst_unused:UNUSED_PAD src0_sel:DWORD src1_sel:BYTE_3
	v_lshlrev_b32_sdwa v172, v230, v172 dst_sel:DWORD dst_unused:UNUSED_PAD src0_sel:DWORD src1_sel:BYTE_3
	v_pk_add_f32 v[180:181], v[218:219], v[180:181]
	v_or_b32_e32 v173, v120, v173
	v_or_b32_e32 v172, v124, v172
	v_mov_b32_e32 v120, v125
	v_add_u32_e32 v119, 0x8000, v180
	v_pk_add_f32 v[124:125], v[120:121], v[172:173]
	v_lshrrev_b32_e32 v119, 16, v119
	v_add_u32_e32 v120, 0x8000, v124
	v_pk_mul_f32 v[138:139], v[224:225], v[224:225]
	v_pk_mul_f32 v[136:137], v[122:123], v[122:123]
	v_and_or_b32 v119, v120, s90, v119
	v_pk_mul_f32 v[120:121], v[124:125], v[124:125]
	v_pk_fma_f32 v[138:139], v[222:223], v[222:223], v[138:139]
	v_pk_fma_f32 v[136:137], v[134:135], v[134:135], v[136:137]
	v_pk_fma_f32 v[172:173], v[180:181], v[180:181], v[120:121]
	v_add_u32_e32 v120, 0x8000, v135
	v_lshrrev_b32_e32 v134, 8, v134
	v_lshrrev_b32_e32 v120, 16, v120
	v_add_u32_e32 v121, 0x8000, v123
	v_perm_b32 v122, v122, v134, s94
	v_add_f32_e32 v134, v138, v170
	v_and_or_b32 v120, v121, s90, v120
	v_add_u32_e32 v121, 0x8000, v181
	v_add_f32_e32 v134, v139, v134
	v_lshrrev_b32_e32 v121, 16, v121
	v_add_u32_e32 v174, 0x8000, v125
	v_add_f32_e32 v134, v171, v134
	v_and_or_b32 v121, v174, s90, v121
	v_lshrrev_b32_e32 v174, 8, v181
	v_lshrrev_b32_e32 v175, 8, v180
	v_add_f32_e32 v134, v136, v134
	v_lshrrev_b32_e32 v176, 8, v241
	v_lshrrev_b32_e32 v177, 8, v240
	v_perm_b32 v124, v124, v175, s94
	v_perm_b32 v125, v125, v174, s94
	v_lshrrev_b32_e32 v135, 8, v135
	v_lshrrev_b32_e32 v174, 8, v223
	v_lshrrev_b32_e32 v175, 8, v222
	v_add_f32_e32 v134, v172, v134
	v_perm_b32 v140, v140, v177, s94
	v_perm_b32 v141, v141, v176, s94
	v_perm_b32 v175, v224, v175, s94
	v_perm_b32 v174, v225, v174, s94
	v_perm_b32 v123, v123, v135, s94
	v_add_f32_e32 v134, v137, v134
	global_store_dwordx4 v[178:179], v[118:121], off offset:256
	v_lshl_or_b32 v125, v125, 16, v123
	v_lshl_or_b32 v124, v124, 16, v122
	v_lshl_add_u64 v[118:119], s[34:35], 0, v[216:217]
	v_lshl_or_b32 v123, v141, 16, v174
	v_lshl_or_b32 v122, v140, 16, v175
	v_add_f32_e32 v134, v173, v134
	v_lshl_add_u64 v[118:119], v[118:119], 0, v[194:195]
	global_store_dwordx4 v[118:119], v[122:125], off
	ds_bpermute_b32 v118, v238, v134
	s_waitcnt lgkmcnt(0)
	v_add_f32_e32 v118, v134, v118
	ds_bpermute_b32 v119, v237, v118
	s_and_saveexec_b64 s[54:55], s[40:41]
	s_mov_b32 s80, 0x4b800000
	s_cbranch_execz .LBB0_1202
	s_waitcnt lgkmcnt(0)
	v_add_f32_e32 v118, v118, v119
	v_fma_f32 v118, v118, s80, 0.5
	v_trunc_f32_e32 v118, v118
	v_mul_f32_e32 v119, 0x2f800000, v118
	v_floor_f32_e32 v119, v119
	v_fmac_f32_e32 v118, 0xcf800000, v119
	v_cvt_u32_f32_e32 v118, v118
	v_cvt_u32_f32_e32 v119, v119
	v_lshl_add_u64 v[120:121], v[198:199], 3, s[44:45]
	global_atomic_add_x2 v[120:121], v[118:119], off
